# up/down/gemm1 K-loops: in 6 of 8 phases the second LDS-DMA piece is issued mid-way through the following MFMA burst instead of the load segment (vmcnt(10)->vmcnt(9))
# baseline (speedup 1.0000x reference)
; #define G8_STAGE(bufoff, gbase) do { _Pragma("unroll") for (int _i = 0; _i < 2; ++_i) \
;     __builtin_amdgcn_global_load_lds((const unsigned*)((const char*)(gbase) + voffA[_i]), (LAS unsigned*)(lds + (bufoff) + ldsw + _i * 8192), 16, 0, 0); } while (0)
; #define G8_LDA(dst, b, h) do { _Pragma("unroll") for (int m = 0; m < 4; ++m) _Pragma("unroll") for (int k = 0; k < 2; ++k) dst[m][k] = *(const LAS h16x8*)(lds + G8_SA(b, h) + aoff + m * 2048 + k * 1024); } while (0)
; #define G8_LDB(dst, b, h) do { _Pragma("unroll") for (int n = 0; n < 2; ++n) _Pragma("unroll") for (int k = 0; k < 2; ++k) dst[n][k] = *(const LAS h16x8*)(lds + G8_SB(b, h) + boff + n * 2048 + k * 1024); } while (0)
; #define G8_MMA(ai, bj, At, Bt_) do { __builtin_amdgcn_s_setprio(1); _Pragma("unroll") for (int m = 0; m < 4; ++m) _Pragma("unroll") for (int n = 0; n < 2; ++n) _Pragma("unroll") for (int k = 0; k < 2; ++k) \
;     acc[ai][bj][m][n] = __builtin_amdgcn_mfma_f32_16x16x32_f16(Bt_[n][k], At[m][k], acc[ai][bj][m][n], 0, 0, 0); __builtin_amdgcn_s_setprio(0); } while (0)
; #define G8_WAIT_V(n) asm volatile("s_waitcnt vmcnt(" #n ")" ::: "memory")
; #define G8_WAIT_L(n) asm volatile("s_waitcnt lgkmcnt(" #n ")" ::: "memory")
; #define G8_BAR __builtin_amdgcn_s_barrier()
; template <class Epi>
; __device__ __forceinline__ void gemm_phase(LAS unsigned char* lds, const h16* A, const h16* Bt, int K, const Order& S, const Epi& E) {
;     ...
;     for (int t = 0; t < nt; t += 2) {
;       const bool last = (t == nt - 2);
;       const char* a1 = cA + (size_t)(t + 1) * kstep;
;       const char* a2 = last ? nA : cA + (size_t)(t + 2) * kstep;
;       const char* b2 = last ? nB : cB + (size_t)(t + 2) * kstep;
;       const char* a3 = a2 + kstep;
;       const char* b3 = b2 + kstep;
;       if (Epi::MID_T >= 0 && t == Epi::MID_T) E.mid(acc, ui, wr, fr);
;       G8_LDB(B0, 0, 0); G8_SCHED; G8_LDA(At, 0, 0); G8_STAGE(G8_SA(1, 1), a1 + hstep);
;       G8_WAIT_L(8); G8_BAR; G8_WAIT_L(0); G8_MMA(0, 0, At, B0); G8_BAR; G8_SCHED;
;       G8_LDB(B1, 0, 1); G8_STAGE(G8_SB(0, 0), b2);
;       G8_BAR; G8_WAIT_L(0); G8_MMA(0, 1, At, B1); G8_BAR;
;       G8_LDA(At, 0, 1); G8_STAGE(G8_SA(0, 0), a2);
;       G8_BAR; G8_WAIT_L(0); G8_MMA(1, 0, At, B0); G8_BAR; G8_SCHED;
;       G8_STAGE(G8_SB(0, 1), b2 + hstep);
;       G8_WAIT_V(6); G8_BAR; G8_MMA(1, 1, At, B1); G8_BAR;
.LBB0_195:
	s_add_u32 s12, s10, 0xfffc0080
	s_addc_u32 s13, s11, -1
	s_cmp_eq_u32 s54, 12
	s_cselect_b32 s15, s19, s13
	s_cselect_b32 s14, s25, s12
	s_cselect_b32 s13, s17, s53
	s_cselect_b32 s12, s26, s27
	s_mov_b32 m0, s50
	v_lshl_add_u64 v[140:141], s[10:11], 0, v[136:137]
	ds_read_b128 v[202:205], v159
	ds_read_b128 v[206:209], v159 offset:1024
	ds_read_b128 v[210:213], v159 offset:2048
	ds_read_b128 v[214:217], v159 offset:3072
	ds_read_b128 v[218:221], v159 offset:4096
	ds_read_b128 v[222:225], v159 offset:5120
	ds_read_b128 v[226:229], v159 offset:6144
	ds_read_b128 v[230:233], v159 offset:7168
	global_load_lds_dwordx4 v[140:141], off
	s_waitcnt lgkmcnt(8)
	s_barrier
	s_waitcnt lgkmcnt(0)
	s_setprio 1
	s_waitcnt lgkmcnt(0)
	v_mfma_f32_16x16x32_f16 v[126:129], v[152:155], v[202:205], v[126:129]
	v_mfma_f32_16x16x32_f16 v[122:125], v[182:185], v[202:205], v[122:125]
	v_mfma_f32_16x16x32_f16 v[110:113], v[152:155], v[210:213], v[110:113]
	v_mfma_f32_16x16x32_f16 v[106:109], v[182:185], v[210:213], v[106:109]
	v_mfma_f32_16x16x32_f16 v[94:97], v[152:155], v[218:221], v[94:97]
	v_mfma_f32_16x16x32_f16 v[90:93], v[182:185], v[218:221], v[90:93]
	v_mfma_f32_16x16x32_f16 v[78:81], v[152:155], v[226:229], v[78:81]
	v_mfma_f32_16x16x32_f16 v[74:77], v[182:185], v[226:229], v[74:77]
	v_lshl_add_u64 v[140:141], s[10:11], 0, v[138:139]
	s_mov_b32 m0, s51
	s_nop 0
	global_load_lds_dwordx4 v[140:141], off
	v_mfma_f32_16x16x32_f16 v[126:129], v[178:181], v[206:209], v[126:129]
	v_mfma_f32_16x16x32_f16 v[122:125], v[186:189], v[206:209], v[122:125]
	v_mfma_f32_16x16x32_f16 v[110:113], v[178:181], v[214:217], v[110:113]
	v_mfma_f32_16x16x32_f16 v[106:109], v[186:189], v[214:217], v[106:109]
	v_mfma_f32_16x16x32_f16 v[94:97], v[178:181], v[222:225], v[94:97]
	v_mfma_f32_16x16x32_f16 v[90:93], v[186:189], v[222:225], v[90:93]
	v_mfma_f32_16x16x32_f16 v[78:81], v[178:181], v[230:233], v[78:81]
	v_mfma_f32_16x16x32_f16 v[74:77], v[186:189], v[230:233], v[74:77]
	s_setprio 0
	s_barrier
	s_mov_b32 m0, s36
	v_lshl_add_u64 v[140:141], s[12:13], 0, v[132:133]
	ds_read_b128 v[234:237], v165
	ds_read_b128 v[238:241], v166
	ds_read_b128 v[242:245], v167
	ds_read_b128 v[246:249], v168
	global_load_lds_dwordx4 v[140:141], off
	s_barrier
	s_waitcnt lgkmcnt(0)
	s_setprio 1
	s_waitcnt lgkmcnt(0)
	v_mfma_f32_16x16x32_f16 v[118:121], v[234:237], v[202:205], v[118:121]
	v_mfma_f32_16x16x32_f16 v[114:117], v[242:245], v[202:205], v[114:117]
	v_mfma_f32_16x16x32_f16 v[102:105], v[234:237], v[210:213], v[102:105]
	v_mfma_f32_16x16x32_f16 v[98:101], v[242:245], v[210:213], v[98:101]
	v_mfma_f32_16x16x32_f16 v[86:89], v[234:237], v[218:221], v[86:89]
	v_mfma_f32_16x16x32_f16 v[82:85], v[242:245], v[218:221], v[82:85]
	v_mfma_f32_16x16x32_f16 v[70:73], v[234:237], v[226:229], v[70:73]
	v_mfma_f32_16x16x32_f16 v[66:69], v[242:245], v[226:229], v[66:69]
	v_lshl_add_u64 v[156:157], s[12:13], 0, v[130:131]
	s_mov_b32 m0, s37
	s_nop 0
	global_load_lds_dwordx4 v[156:157], off
	v_mfma_f32_16x16x32_f16 v[118:121], v[238:241], v[206:209], v[118:121]
	v_mfma_f32_16x16x32_f16 v[114:117], v[246:249], v[206:209], v[114:117]
	v_mfma_f32_16x16x32_f16 v[102:105], v[238:241], v[214:217], v[102:105]
	v_mfma_f32_16x16x32_f16 v[98:101], v[246:249], v[214:217], v[98:101]
	v_mfma_f32_16x16x32_f16 v[86:89], v[238:241], v[222:225], v[86:89]
	v_mfma_f32_16x16x32_f16 v[82:85], v[246:249], v[222:225], v[82:85]
	v_mfma_f32_16x16x32_f16 v[70:73], v[238:241], v[230:233], v[70:73]
	v_mfma_f32_16x16x32_f16 v[66:69], v[246:249], v[230:233], v[66:69]
	s_setprio 0
	s_mov_b32 m0, s35
	v_lshl_add_u64 v[250:251], s[14:15], 0, v[132:133]
	s_barrier
	ds_read_b128 v[202:205], v159 offset:16384
	ds_read_b128 v[206:209], v159 offset:17408
	ds_read_b128 v[210:213], v159 offset:18432
	ds_read_b128 v[214:217], v159 offset:19456
	ds_read_b128 v[218:221], v159 offset:20480
	ds_read_b128 v[222:225], v159 offset:21504
	ds_read_b128 v[226:229], v159 offset:22528
	ds_read_b128 v[230:233], v159 offset:23552
	global_load_lds_dwordx4 v[250:251], off
	s_waitcnt vmcnt(9)
	s_barrier
	s_waitcnt lgkmcnt(0)
	s_setprio 1
	s_waitcnt lgkmcnt(0)
	v_mfma_f32_16x16x32_f16 v[62:65], v[152:155], v[202:205], v[62:65]
	v_mfma_f32_16x16x32_f16 v[58:61], v[182:185], v[202:205], v[58:61]
	v_mfma_f32_16x16x32_f16 v[46:49], v[152:155], v[210:213], v[46:49]
	v_mfma_f32_16x16x32_f16 v[42:45], v[182:185], v[210:213], v[42:45]
	v_mfma_f32_16x16x32_f16 v[30:33], v[152:155], v[218:221], v[30:33]
	v_mfma_f32_16x16x32_f16 v[26:29], v[182:185], v[218:221], v[26:29]
	v_mfma_f32_16x16x32_f16 v[14:17], v[152:155], v[226:229], v[14:17]
	v_mfma_f32_16x16x32_f16 v[10:13], v[182:185], v[226:229], v[10:13]
	v_lshl_add_u64 v[252:253], s[14:15], 0, v[130:131]
	s_mov_b32 m0, s38
	s_nop 0
	global_load_lds_dwordx4 v[252:253], off
	v_mfma_f32_16x16x32_f16 v[62:65], v[178:181], v[206:209], v[62:65]
	v_mfma_f32_16x16x32_f16 v[58:61], v[186:189], v[206:209], v[58:61]
	v_mfma_f32_16x16x32_f16 v[46:49], v[178:181], v[214:217], v[46:49]
	v_mfma_f32_16x16x32_f16 v[42:45], v[186:189], v[214:217], v[42:45]
	v_mfma_f32_16x16x32_f16 v[30:33], v[178:181], v[222:225], v[30:33]
	v_mfma_f32_16x16x32_f16 v[26:29], v[186:189], v[222:225], v[26:29]
	v_mfma_f32_16x16x32_f16 v[14:17], v[178:181], v[230:233], v[14:17]
	v_mfma_f32_16x16x32_f16 v[10:13], v[186:189], v[230:233], v[10:13]
	s_setprio 0
	s_barrier
	s_add_u32 s56, s12, 0x40000
	s_addc_u32 s57, s13, 0
	s_mov_b32 m0, s39
	v_lshl_add_u64 v[152:153], s[56:57], 0, v[132:133]
	global_load_lds_dwordx4 v[152:153], off
	v_lshl_add_u64 v[152:153], s[56:57], 0, v[130:131]
	s_mov_b32 m0, s40
	s_nop 0
	global_load_lds_dwordx4 v[152:153], off
	ds_read_b128 v[152:155], v169
	ds_read_b128 v[178:181], v170
	ds_read_b128 v[182:185], v171
	ds_read_b128 v[186:189], v172
	s_waitcnt vmcnt(6)
	s_barrier
; #define G8_STAGE(bufoff, gbase) do { _Pragma("unroll") for (int _i = 0; _i < 2; ++_i) \
;     __builtin_amdgcn_global_load_lds((const unsigned*)((const char*)(gbase) + voffA[_i]), (LAS unsigned*)(lds + (bufoff) + ldsw + _i * 8192), 16, 0, 0); } while (0)
; #define G8_LDA(dst, b, h) do { _Pragma("unroll") for (int m = 0; m < 4; ++m) _Pragma("unroll") for (int k = 0; k < 2; ++k) dst[m][k] = *(const LAS h16x8*)(lds + G8_SA(b, h) + aoff + m * 2048 + k * 1024); } while (0)
; #define G8_LDB(dst, b, h) do { _Pragma("unroll") for (int n = 0; n < 2; ++n) _Pragma("unroll") for (int k = 0; k < 2; ++k) dst[n][k] = *(const LAS h16x8*)(lds + G8_SB(b, h) + boff + n * 2048 + k * 1024); } while (0)
; #define G8_MMA(ai, bj, At, Bt_) do { __builtin_amdgcn_s_setprio(1); _Pragma("unroll") for (int m = 0; m < 4; ++m) _Pragma("unroll") for (int n = 0; n < 2; ++n) _Pragma("unroll") for (int k = 0; k < 2; ++k) \
;     acc[ai][bj][m][n] = __builtin_amdgcn_mfma_f32_16x16x32_f16(Bt_[n][k], At[m][k], acc[ai][bj][m][n], 0, 0, 0); __builtin_amdgcn_s_setprio(0); } while (0)
; #define G8_WAIT_V(n) asm volatile("s_waitcnt vmcnt(" #n ")" ::: "memory")
; #define G8_WAIT_L(n) asm volatile("s_waitcnt lgkmcnt(" #n ")" ::: "memory")
; #define G8_BAR __builtin_amdgcn_s_barrier()
; #define G8_SCHED __builtin_amdgcn_sched_barrier(0)
; template <class Epi>
; __device__ __forceinline__ void gemm_phase(LAS unsigned char* lds, const h16* A, const h16* Bt, int K, const Order& S, const Epi& E) {
;     ...
;       G8_WAIT_V(6); G8_BAR; G8_MMA(1, 1, At, B1); G8_BAR;
;       G8_LDB(B0, 1, 0); G8_SCHED; G8_LDA(At, 1, 0); G8_STAGE(G8_SA(0, 1), a2 + hstep);
;       G8_WAIT_L(8); G8_BAR; G8_WAIT_L(0); G8_MMA(0, 0, At, B0); G8_BAR; G8_SCHED;
;       G8_LDB(B1, 1, 1); G8_STAGE(G8_SB(1, 0), b3);
;       G8_BAR; G8_WAIT_L(0); G8_MMA(0, 1, At, B1); G8_BAR;
;       G8_LDA(At, 1, 1); G8_STAGE(G8_SA(1, 0), a3);
	s_setprio 1
	v_mfma_f32_16x16x32_f16 v[54:57], v[234:237], v[202:205], v[54:57]
	v_mfma_f32_16x16x32_f16 v[50:53], v[242:245], v[202:205], v[50:53]
	v_mfma_f32_16x16x32_f16 v[38:41], v[234:237], v[210:213], v[38:41]
	v_mfma_f32_16x16x32_f16 v[34:37], v[242:245], v[210:213], v[34:37]
	v_mfma_f32_16x16x32_f16 v[22:25], v[234:237], v[218:221], v[22:25]
	v_mfma_f32_16x16x32_f16 v[18:21], v[242:245], v[218:221], v[18:21]
	v_mfma_f32_16x16x32_f16 v[6:9], v[234:237], v[226:229], v[6:9]
	v_mfma_f32_16x16x32_f16 v[2:5], v[242:245], v[226:229], v[2:5]
	v_mfma_f32_16x16x32_f16 v[54:57], v[238:241], v[206:209], v[54:57]
	v_mfma_f32_16x16x32_f16 v[50:53], v[246:249], v[206:209], v[50:53]
	v_mfma_f32_16x16x32_f16 v[38:41], v[238:241], v[214:217], v[38:41]
	v_mfma_f32_16x16x32_f16 v[34:37], v[246:249], v[214:217], v[34:37]
	v_mfma_f32_16x16x32_f16 v[22:25], v[238:241], v[222:225], v[22:25]
	v_mfma_f32_16x16x32_f16 v[18:21], v[246:249], v[222:225], v[18:21]
	v_mfma_f32_16x16x32_f16 v[6:9], v[238:241], v[230:233], v[6:9]
	v_mfma_f32_16x16x32_f16 v[2:5], v[246:249], v[230:233], v[2:5]
	s_setprio 0
	s_barrier
	s_add_u32 s14, s14, 0x40000
	s_addc_u32 s15, s15, 0
	s_mov_b32 m0, s41
	v_lshl_add_u64 v[234:235], s[14:15], 0, v[132:133]
	ds_read_b128 v[202:205], v159 offset:32768
	ds_read_b128 v[206:209], v159 offset:33792
	ds_read_b128 v[210:213], v159 offset:34816
	ds_read_b128 v[214:217], v159 offset:35840
	ds_read_b128 v[218:221], v159 offset:36864
	ds_read_b128 v[222:225], v159 offset:37888
	ds_read_b128 v[226:229], v159 offset:38912
	ds_read_b128 v[230:233], v159 offset:39936
	global_load_lds_dwordx4 v[234:235], off
	s_waitcnt lgkmcnt(8)
	s_barrier
	s_waitcnt lgkmcnt(0)
	s_setprio 1
	s_waitcnt lgkmcnt(0)
	v_mfma_f32_16x16x32_f16 v[126:129], v[152:155], v[202:205], v[126:129]
	v_mfma_f32_16x16x32_f16 v[122:125], v[182:185], v[202:205], v[122:125]
	v_mfma_f32_16x16x32_f16 v[110:113], v[152:155], v[210:213], v[110:113]
	v_mfma_f32_16x16x32_f16 v[106:109], v[182:185], v[210:213], v[106:109]
	v_mfma_f32_16x16x32_f16 v[94:97], v[152:155], v[218:221], v[94:97]
	v_mfma_f32_16x16x32_f16 v[90:93], v[182:185], v[218:221], v[90:93]
	v_mfma_f32_16x16x32_f16 v[78:81], v[152:155], v[226:229], v[78:81]
	v_mfma_f32_16x16x32_f16 v[74:77], v[182:185], v[226:229], v[74:77]
	v_lshl_add_u64 v[234:235], s[14:15], 0, v[130:131]
	s_mov_b32 m0, s42
	s_nop 0
	global_load_lds_dwordx4 v[234:235], off
	v_mfma_f32_16x16x32_f16 v[126:129], v[178:181], v[206:209], v[126:129]
	v_mfma_f32_16x16x32_f16 v[122:125], v[186:189], v[206:209], v[122:125]
	v_mfma_f32_16x16x32_f16 v[110:113], v[178:181], v[214:217], v[110:113]
	v_mfma_f32_16x16x32_f16 v[106:109], v[186:189], v[214:217], v[106:109]
	v_mfma_f32_16x16x32_f16 v[94:97], v[178:181], v[222:225], v[94:97]
	v_mfma_f32_16x16x32_f16 v[90:93], v[186:189], v[222:225], v[90:93]
	v_mfma_f32_16x16x32_f16 v[78:81], v[178:181], v[230:233], v[78:81]
	v_mfma_f32_16x16x32_f16 v[74:77], v[186:189], v[230:233], v[74:77]
	s_setprio 0
	s_barrier
	s_mov_b32 m0, s44
	v_lshl_add_u64 v[140:141], v[140:141], 0, s[94:95]
	ds_read_b128 v[234:237], v173
	ds_read_b128 v[238:241], v174
	ds_read_b128 v[242:245], v175
	ds_read_b128 v[246:249], v176
	global_load_lds_dwordx4 v[140:141], off
	s_barrier
	s_waitcnt lgkmcnt(0)
	s_setprio 1
	s_waitcnt lgkmcnt(0)
	v_mfma_f32_16x16x32_f16 v[118:121], v[234:237], v[202:205], v[118:121]
	v_mfma_f32_16x16x32_f16 v[114:117], v[242:245], v[202:205], v[114:117]
	v_mfma_f32_16x16x32_f16 v[102:105], v[234:237], v[210:213], v[102:105]
	v_mfma_f32_16x16x32_f16 v[98:101], v[242:245], v[210:213], v[98:101]
	v_mfma_f32_16x16x32_f16 v[86:89], v[234:237], v[218:221], v[86:89]
	v_mfma_f32_16x16x32_f16 v[82:85], v[242:245], v[218:221], v[82:85]
	v_mfma_f32_16x16x32_f16 v[70:73], v[234:237], v[226:229], v[70:73]
	v_mfma_f32_16x16x32_f16 v[66:69], v[242:245], v[226:229], v[66:69]
	v_lshl_add_u64 v[140:141], v[156:157], 0, s[94:95]
	s_mov_b32 m0, s45
	s_nop 0
	global_load_lds_dwordx4 v[140:141], off
	v_mfma_f32_16x16x32_f16 v[118:121], v[238:241], v[206:209], v[118:121]
	v_mfma_f32_16x16x32_f16 v[114:117], v[246:249], v[206:209], v[114:117]
	v_mfma_f32_16x16x32_f16 v[102:105], v[238:241], v[214:217], v[102:105]
	v_mfma_f32_16x16x32_f16 v[98:101], v[246:249], v[214:217], v[98:101]
	v_mfma_f32_16x16x32_f16 v[86:89], v[238:241], v[222:225], v[86:89]
	v_mfma_f32_16x16x32_f16 v[82:85], v[246:249], v[222:225], v[82:85]
	v_mfma_f32_16x16x32_f16 v[70:73], v[238:241], v[230:233], v[70:73]
	v_mfma_f32_16x16x32_f16 v[66:69], v[246:249], v[230:233], v[66:69]
	s_setprio 0
	s_mov_b32 m0, s46
	v_lshl_add_u64 v[140:141], v[250:251], 0, s[94:95]
	s_barrier
; #define G8_STAGE(bufoff, gbase) do { _Pragma("unroll") for (int _i = 0; _i < 2; ++_i) \
;     __builtin_amdgcn_global_load_lds((const unsigned*)((const char*)(gbase) + voffA[_i]), (LAS unsigned*)(lds + (bufoff) + ldsw + _i * 8192), 16, 0, 0); } while (0)
; #define G8_LDA(dst, b, h) do { _Pragma("unroll") for (int m = 0; m < 4; ++m) _Pragma("unroll") for (int k = 0; k < 2; ++k) dst[m][k] = *(const LAS h16x8*)(lds + G8_SA(b, h) + aoff + m * 2048 + k * 1024); } while (0)
; #define G8_MMA(ai, bj, At, Bt_) do { __builtin_amdgcn_s_setprio(1); _Pragma("unroll") for (int m = 0; m < 4; ++m) _Pragma("unroll") for (int n = 0; n < 2; ++n) _Pragma("unroll") for (int k = 0; k < 2; ++k) \
;     acc[ai][bj][m][n] = __builtin_amdgcn_mfma_f32_16x16x32_f16(Bt_[n][k], At[m][k], acc[ai][bj][m][n], 0, 0, 0); __builtin_amdgcn_s_setprio(0); } while (0)
; #define G8_WAIT_V(n) asm volatile("s_waitcnt vmcnt(" #n ")" ::: "memory")
; #define G8_WAIT_L(n) asm volatile("s_waitcnt lgkmcnt(" #n ")" ::: "memory")
; #define G8_BAR __builtin_amdgcn_s_barrier()
; #define G8_SCHED __builtin_amdgcn_sched_barrier(0)
; template <class Epi>
; __device__ __forceinline__ void gemm_phase(LAS unsigned char* lds, const h16* A, const h16* Bt, int K, const Order& S, const Epi& E) {
;     ...
;       G8_LDA(At, 1, 1); G8_STAGE(G8_SA(1, 0), a3);
;       G8_BAR; G8_WAIT_L(0); G8_MMA(1, 0, At, B0); G8_BAR; G8_SCHED;
;       G8_STAGE(G8_SB(1, 1), b3 + hstep);
;       G8_WAIT_V(6); G8_BAR; G8_MMA(1, 1, At, B1); G8_BAR;
;     }
;     E(acc, cur, ui, wr, wc, fr, fq);
;   __device__ __forceinline__ void operator()(const f32x4 (&acc)[2][2][4][2], const g8::Unit& u, int ui, int wr, int wc, int fr, int fq) const {
;     const int hs = u.pn * 4 + wc;
;     int gi = -1;
;     if (hs < 4) gi = 0; else if (hs < 6) gi = 1; else if (hs >= 16 && hs < 20) gi = 2; else if (hs == 22) gi = 4; else if (hs == 24) gi = 5;
	ds_read_b128 v[202:205], v159 offset:49152
	ds_read_b128 v[206:209], v159 offset:50176
	ds_read_b128 v[210:213], v159 offset:51200
	ds_read_b128 v[214:217], v159 offset:52224
	ds_read_b128 v[218:221], v159 offset:53248
	ds_read_b128 v[222:225], v159 offset:54272
	ds_read_b128 v[226:229], v159 offset:55296
	ds_read_b128 v[230:233], v159 offset:56320
	global_load_lds_dwordx4 v[140:141], off
	s_waitcnt vmcnt(9)
	s_barrier
	s_waitcnt lgkmcnt(0)
	s_setprio 1
	s_waitcnt lgkmcnt(0)
	v_mfma_f32_16x16x32_f16 v[62:65], v[152:155], v[202:205], v[62:65]
	v_mfma_f32_16x16x32_f16 v[58:61], v[182:185], v[202:205], v[58:61]
	v_mfma_f32_16x16x32_f16 v[46:49], v[152:155], v[210:213], v[46:49]
	v_mfma_f32_16x16x32_f16 v[42:45], v[182:185], v[210:213], v[42:45]
	v_mfma_f32_16x16x32_f16 v[30:33], v[152:155], v[218:221], v[30:33]
	v_mfma_f32_16x16x32_f16 v[26:29], v[182:185], v[218:221], v[26:29]
	v_mfma_f32_16x16x32_f16 v[14:17], v[152:155], v[226:229], v[14:17]
	v_mfma_f32_16x16x32_f16 v[10:13], v[182:185], v[226:229], v[10:13]
	v_lshl_add_u64 v[140:141], v[252:253], 0, s[94:95]
	s_mov_b32 m0, s47
	s_nop 0
	global_load_lds_dwordx4 v[140:141], off
	v_mfma_f32_16x16x32_f16 v[62:65], v[178:181], v[206:209], v[62:65]
	v_mfma_f32_16x16x32_f16 v[58:61], v[186:189], v[206:209], v[58:61]
	v_mfma_f32_16x16x32_f16 v[46:49], v[178:181], v[214:217], v[46:49]
	v_mfma_f32_16x16x32_f16 v[42:45], v[186:189], v[214:217], v[42:45]
	v_mfma_f32_16x16x32_f16 v[30:33], v[178:181], v[222:225], v[30:33]
	v_mfma_f32_16x16x32_f16 v[26:29], v[186:189], v[222:225], v[26:29]
	v_mfma_f32_16x16x32_f16 v[14:17], v[178:181], v[230:233], v[14:17]
	v_mfma_f32_16x16x32_f16 v[10:13], v[186:189], v[230:233], v[10:13]
	s_setprio 0
	s_barrier
	s_add_u32 s12, s12, 0x40080
	s_addc_u32 s13, s13, 0
	s_mov_b32 m0, s48
	v_lshl_add_u64 v[140:141], s[12:13], 0, v[132:133]
	global_load_lds_dwordx4 v[140:141], off
	v_lshl_add_u64 v[140:141], s[12:13], 0, v[130:131]
	s_mov_b32 m0, s49
	s_nop 0
	global_load_lds_dwordx4 v[140:141], off
	ds_read_b128 v[152:155], v161
	ds_read_b128 v[178:181], v162
	ds_read_b128 v[182:185], v163
	ds_read_b128 v[186:189], v164
	s_waitcnt vmcnt(6)
	s_barrier
	s_setprio 1
	v_mfma_f32_16x16x32_f16 v[54:57], v[234:237], v[202:205], v[54:57]
	v_mfma_f32_16x16x32_f16 v[50:53], v[242:245], v[202:205], v[50:53]
	v_mfma_f32_16x16x32_f16 v[38:41], v[234:237], v[210:213], v[38:41]
	v_mfma_f32_16x16x32_f16 v[34:37], v[242:245], v[210:213], v[34:37]
	v_mfma_f32_16x16x32_f16 v[22:25], v[234:237], v[218:221], v[22:25]
	v_mfma_f32_16x16x32_f16 v[18:21], v[242:245], v[218:221], v[18:21]
	v_mfma_f32_16x16x32_f16 v[6:9], v[234:237], v[226:229], v[6:9]
	v_mfma_f32_16x16x32_f16 v[2:5], v[242:245], v[226:229], v[2:5]
	v_mfma_f32_16x16x32_f16 v[54:57], v[238:241], v[206:209], v[54:57]
	v_mfma_f32_16x16x32_f16 v[50:53], v[246:249], v[206:209], v[50:53]
	v_mfma_f32_16x16x32_f16 v[38:41], v[238:241], v[214:217], v[38:41]
	v_mfma_f32_16x16x32_f16 v[34:37], v[246:249], v[214:217], v[34:37]
	v_mfma_f32_16x16x32_f16 v[22:25], v[238:241], v[222:225], v[22:25]
	v_mfma_f32_16x16x32_f16 v[18:21], v[246:249], v[222:225], v[18:21]
	v_mfma_f32_16x16x32_f16 v[6:9], v[238:241], v[230:233], v[6:9]
	v_mfma_f32_16x16x32_f16 v[2:5], v[246:249], v[230:233], v[2:5]
	s_setprio 0
	s_add_i32 s54, s54, 2
	s_add_u32 s10, s10, 0x100
	s_addc_u32 s11, s11, 0
	s_add_u32 s27, s27, 0x100
	s_addc_u32 s53, s53, 0
	s_cmp_gt_u32 s54, 13
	s_barrier
	s_cbranch_scc0 .LBB0_195
	s_waitcnt lgkmcnt(0)
	s_lshl_b32 s10, s24, 2
	s_or_b32 s19, s10, s43
	s_cmp_lt_i32 s19, 4
	s_cbranch_scc1 .LBB0_203
	s_cmp_lt_u32 s19, 6
	s_cbranch_scc1 .LBB0_204
	s_cmp_eq_u32 s24, 4
	s_cbranch_scc1 .LBB0_205
	s_cmp_lt_i32 s19, 24
	s_cbranch_scc1 .LBB0_206
	s_cmp_eq_u32 s19, 24
	s_mov_b64 s[10:11], -1
	s_cbranch_scc0 .LBB0_202
	s_mov_b64 s[10:11], 0

; #define G8_STAGE(bufoff, gbase) do { _Pragma("unroll") for (int _i = 0; _i < 2; ++_i) \
;     __builtin_amdgcn_global_load_lds((const unsigned*)((const char*)(gbase) + voffA[_i]), (LAS unsigned*)(lds + (bufoff) + ldsw + _i * 8192), 16, 0, 0); } while (0)
; #define G8_LDA(dst, b, h) do { _Pragma("unroll") for (int m = 0; m < 4; ++m) _Pragma("unroll") for (int k = 0; k < 2; ++k) dst[m][k] = *(const LAS h16x8*)(lds + G8_SA(b, h) + aoff + m * 2048 + k * 1024); } while (0)
; #define G8_LDB(dst, b, h) do { _Pragma("unroll") for (int n = 0; n < 2; ++n) _Pragma("unroll") for (int k = 0; k < 2; ++k) dst[n][k] = *(const LAS h16x8*)(lds + G8_SB(b, h) + boff + n * 2048 + k * 1024); } while (0)
; #define G8_MMA(ai, bj, At, Bt_) do { __builtin_amdgcn_s_setprio(1); _Pragma("unroll") for (int m = 0; m < 4; ++m) _Pragma("unroll") for (int n = 0; n < 2; ++n) _Pragma("unroll") for (int k = 0; k < 2; ++k) \
;     acc[ai][bj][m][n] = __builtin_amdgcn_mfma_f32_16x16x32_f16(Bt_[n][k], At[m][k], acc[ai][bj][m][n], 0, 0, 0); __builtin_amdgcn_s_setprio(0); } while (0)
; #define G8_WAIT_V(n) asm volatile("s_waitcnt vmcnt(" #n ")" ::: "memory")
; #define G8_WAIT_L(n) asm volatile("s_waitcnt lgkmcnt(" #n ")" ::: "memory")
; #define G8_BAR __builtin_amdgcn_s_barrier()
; template <class Epi>
; __device__ __forceinline__ void gemm_phase(LAS unsigned char* lds, const h16* A, const h16* Bt, int K, const Order& S, const Epi& E) {
;     ...
;     for (int t = 0; t < nt; t += 2) {
;       const bool last = (t == nt - 2);
;       const char* a1 = cA + (size_t)(t + 1) * kstep;
;       const char* a2 = last ? nA : cA + (size_t)(t + 2) * kstep;
;       const char* b2 = last ? nB : cB + (size_t)(t + 2) * kstep;
;       const char* a3 = a2 + kstep;
;       const char* b3 = b2 + kstep;
;       if (Epi::MID_T >= 0 && t == Epi::MID_T) E.mid(acc, ui, wr, fr);
;       G8_LDB(B0, 0, 0); G8_SCHED; G8_LDA(At, 0, 0); G8_STAGE(G8_SA(1, 1), a1 + hstep);
;       G8_WAIT_L(8); G8_BAR; G8_WAIT_L(0); G8_MMA(0, 0, At, B0); G8_BAR; G8_SCHED;
;       G8_LDB(B1, 0, 1); G8_STAGE(G8_SB(0, 0), b2);
;       G8_BAR; G8_WAIT_L(0); G8_MMA(0, 1, At, B1); G8_BAR;
;       G8_LDA(At, 0, 1); G8_STAGE(G8_SA(0, 0), a2);
;       G8_BAR; G8_WAIT_L(0); G8_MMA(1, 0, At, B0); G8_BAR; G8_SCHED;
;       G8_STAGE(G8_SB(0, 1), b2 + hstep);
;       G8_WAIT_V(6); G8_BAR; G8_MMA(1, 1, At, B1); G8_BAR;
.LBB0_2473:
	s_add_u32 s20, s18, 0xfffc0080
	s_addc_u32 s21, s19, -1
	s_cmp_eq_u32 s51, 12
	s_cselect_b32 s23, s13, s21
	s_cselect_b32 s22, s47, s20
	s_cselect_b32 s21, s11, s50
	s_cselect_b32 s20, s48, s49
	v_lshl_add_u64 v[188:189], s[18:19], 0, v[134:135]
	s_add_i32 m0, s27, 0xc000
	ds_read_b128 v[176:179], v139
	ds_read_b128 v[180:183], v139 offset:1024
	ds_read_b128 v[184:187], v139 offset:2048
	ds_read_b128 v[202:205], v139 offset:3072
	ds_read_b128 v[206:209], v139 offset:4096
	ds_read_b128 v[210:213], v139 offset:5120
	ds_read_b128 v[214:217], v139 offset:6144
	ds_read_b128 v[218:221], v139 offset:7168
	global_load_lds_dwordx4 v[188:189], off
	s_waitcnt lgkmcnt(8)
	s_barrier
	s_waitcnt lgkmcnt(0)
	s_setprio 1
	s_waitcnt lgkmcnt(0)
	v_mfma_f32_16x16x32_f16 v[126:129], v[160:163], v[176:179], v[126:129]
	v_mfma_f32_16x16x32_f16 v[122:125], v[168:171], v[176:179], v[122:125]
	v_mfma_f32_16x16x32_f16 v[110:113], v[160:163], v[184:187], v[110:113]
	v_mfma_f32_16x16x32_f16 v[106:109], v[168:171], v[184:187], v[106:109]
	v_mfma_f32_16x16x32_f16 v[94:97], v[160:163], v[206:209], v[94:97]
	v_mfma_f32_16x16x32_f16 v[90:93], v[168:171], v[206:209], v[90:93]
	v_mfma_f32_16x16x32_f16 v[78:81], v[160:163], v[214:217], v[78:81]
	v_mfma_f32_16x16x32_f16 v[74:77], v[168:171], v[214:217], v[74:77]
	v_lshl_add_u64 v[188:189], s[18:19], 0, v[136:137]
	s_add_i32 m0, s27, 0xe000
	s_nop 0
	global_load_lds_dwordx4 v[188:189], off
	v_mfma_f32_16x16x32_f16 v[126:129], v[164:167], v[180:183], v[126:129]
	v_mfma_f32_16x16x32_f16 v[122:125], v[172:175], v[180:183], v[122:125]
	v_mfma_f32_16x16x32_f16 v[110:113], v[164:167], v[202:205], v[110:113]
	v_mfma_f32_16x16x32_f16 v[106:109], v[172:175], v[202:205], v[106:109]
	v_mfma_f32_16x16x32_f16 v[94:97], v[164:167], v[210:213], v[94:97]
	v_mfma_f32_16x16x32_f16 v[90:93], v[172:175], v[210:213], v[90:93]
	v_mfma_f32_16x16x32_f16 v[78:81], v[164:167], v[218:221], v[78:81]
	v_mfma_f32_16x16x32_f16 v[74:77], v[172:175], v[218:221], v[74:77]
	s_setprio 0
	s_barrier
	v_or_b32_e32 v159, 0x14000, v140
	v_add_u32_e32 v188, 0x14400, v140
	ds_read_b128 v[222:225], v159
	ds_read_b128 v[226:229], v188
	v_add_u32_e32 v159, 0x14800, v140
	v_add_u32_e32 v188, 0x14c00, v140
	s_mov_b32 m0, s28
	ds_read_b128 v[230:233], v159
	ds_read_b128 v[234:237], v188
	v_lshl_add_u64 v[188:189], s[20:21], 0, v[132:133]
	global_load_lds_dwordx4 v[188:189], off
	s_barrier
	s_waitcnt lgkmcnt(0)
	s_setprio 1
	s_waitcnt lgkmcnt(0)
	v_mfma_f32_16x16x32_f16 v[118:121], v[222:225], v[176:179], v[118:121]
	v_mfma_f32_16x16x32_f16 v[114:117], v[230:233], v[176:179], v[114:117]
	v_mfma_f32_16x16x32_f16 v[102:105], v[222:225], v[184:187], v[102:105]
	v_mfma_f32_16x16x32_f16 v[98:101], v[230:233], v[184:187], v[98:101]
	v_mfma_f32_16x16x32_f16 v[86:89], v[222:225], v[206:209], v[86:89]
	v_mfma_f32_16x16x32_f16 v[82:85], v[230:233], v[206:209], v[82:85]
	v_mfma_f32_16x16x32_f16 v[70:73], v[222:225], v[214:217], v[70:73]
	v_mfma_f32_16x16x32_f16 v[66:69], v[230:233], v[214:217], v[66:69]
	v_lshl_add_u64 v[238:239], s[20:21], 0, v[130:131]
	s_mov_b32 m0, s29
	s_nop 0
	global_load_lds_dwordx4 v[238:239], off
	v_mfma_f32_16x16x32_f16 v[118:121], v[226:229], v[180:183], v[118:121]
	v_mfma_f32_16x16x32_f16 v[114:117], v[234:237], v[180:183], v[114:117]
	v_mfma_f32_16x16x32_f16 v[102:105], v[226:229], v[202:205], v[102:105]
	v_mfma_f32_16x16x32_f16 v[98:101], v[234:237], v[202:205], v[98:101]
	v_mfma_f32_16x16x32_f16 v[86:89], v[226:229], v[210:213], v[86:89]
	v_mfma_f32_16x16x32_f16 v[82:85], v[234:237], v[210:213], v[82:85]
	v_mfma_f32_16x16x32_f16 v[70:73], v[226:229], v[218:221], v[70:73]
	v_mfma_f32_16x16x32_f16 v[66:69], v[234:237], v[218:221], v[66:69]
	s_setprio 0
	s_mov_b32 m0, s27
	v_lshl_add_u64 v[240:241], s[22:23], 0, v[132:133]
	s_barrier
	ds_read_b128 v[176:179], v139 offset:16384
	ds_read_b128 v[180:183], v139 offset:17408
	ds_read_b128 v[184:187], v139 offset:18432
	ds_read_b128 v[202:205], v139 offset:19456
	ds_read_b128 v[206:209], v139 offset:20480
	ds_read_b128 v[210:213], v139 offset:21504
	ds_read_b128 v[214:217], v139 offset:22528
	ds_read_b128 v[218:221], v139 offset:23552
	global_load_lds_dwordx4 v[240:241], off
	s_waitcnt vmcnt(9)
	s_barrier
	s_waitcnt lgkmcnt(0)
	s_setprio 1
	s_waitcnt lgkmcnt(0)
	v_mfma_f32_16x16x32_f16 v[62:65], v[160:163], v[176:179], v[62:65]
	v_mfma_f32_16x16x32_f16 v[58:61], v[168:171], v[176:179], v[58:61]
	v_mfma_f32_16x16x32_f16 v[46:49], v[160:163], v[184:187], v[46:49]
	v_mfma_f32_16x16x32_f16 v[42:45], v[168:171], v[184:187], v[42:45]
	v_mfma_f32_16x16x32_f16 v[30:33], v[160:163], v[206:209], v[30:33]
	v_mfma_f32_16x16x32_f16 v[26:29], v[168:171], v[206:209], v[26:29]
	v_mfma_f32_16x16x32_f16 v[14:17], v[160:163], v[214:217], v[14:17]
	v_mfma_f32_16x16x32_f16 v[10:13], v[168:171], v[214:217], v[10:13]
	v_lshl_add_u64 v[242:243], s[22:23], 0, v[130:131]
	s_mov_b32 m0, s30
	s_nop 0
	global_load_lds_dwordx4 v[242:243], off
	v_mfma_f32_16x16x32_f16 v[62:65], v[164:167], v[180:183], v[62:65]
	v_mfma_f32_16x16x32_f16 v[58:61], v[172:175], v[180:183], v[58:61]
	v_mfma_f32_16x16x32_f16 v[46:49], v[164:167], v[202:205], v[46:49]
	v_mfma_f32_16x16x32_f16 v[42:45], v[172:175], v[202:205], v[42:45]
	v_mfma_f32_16x16x32_f16 v[30:33], v[164:167], v[210:213], v[30:33]
	v_mfma_f32_16x16x32_f16 v[26:29], v[172:175], v[210:213], v[26:29]
	v_mfma_f32_16x16x32_f16 v[14:17], v[164:167], v[218:221], v[14:17]
	v_mfma_f32_16x16x32_f16 v[10:13], v[172:175], v[218:221], v[10:13]
	s_setprio 0
	s_barrier
; #define G8_STAGE(bufoff, gbase) do { _Pragma("unroll") for (int _i = 0; _i < 2; ++_i) \
;     __builtin_amdgcn_global_load_lds((const unsigned*)((const char*)(gbase) + voffA[_i]), (LAS unsigned*)(lds + (bufoff) + ldsw + _i * 8192), 16, 0, 0); } while (0)
; #define G8_LDA(dst, b, h) do { _Pragma("unroll") for (int m = 0; m < 4; ++m) _Pragma("unroll") for (int k = 0; k < 2; ++k) dst[m][k] = *(const LAS h16x8*)(lds + G8_SA(b, h) + aoff + m * 2048 + k * 1024); } while (0)
; #define G8_LDB(dst, b, h) do { _Pragma("unroll") for (int n = 0; n < 2; ++n) _Pragma("unroll") for (int k = 0; k < 2; ++k) dst[n][k] = *(const LAS h16x8*)(lds + G8_SB(b, h) + boff + n * 2048 + k * 1024); } while (0)
; #define G8_MMA(ai, bj, At, Bt_) do { __builtin_amdgcn_s_setprio(1); _Pragma("unroll") for (int m = 0; m < 4; ++m) _Pragma("unroll") for (int n = 0; n < 2; ++n) _Pragma("unroll") for (int k = 0; k < 2; ++k) \
;     acc[ai][bj][m][n] = __builtin_amdgcn_mfma_f32_16x16x32_f16(Bt_[n][k], At[m][k], acc[ai][bj][m][n], 0, 0, 0); __builtin_amdgcn_s_setprio(0); } while (0)
; #define G8_WAIT_V(n) asm volatile("s_waitcnt vmcnt(" #n ")" ::: "memory")
; #define G8_WAIT_L(n) asm volatile("s_waitcnt lgkmcnt(" #n ")" ::: "memory")
; #define G8_BAR __builtin_amdgcn_s_barrier()
; #define G8_SCHED __builtin_amdgcn_sched_barrier(0)
; template <class Epi>
; __device__ __forceinline__ void gemm_phase(LAS unsigned char* lds, const h16* A, const h16* Bt, int K, const Order& S, const Epi& E) {
;     ...
;       G8_WAIT_V(6); G8_BAR; G8_MMA(1, 1, At, B1); G8_BAR;
;       G8_LDB(B0, 1, 0); G8_SCHED; G8_LDA(At, 1, 0); G8_STAGE(G8_SA(0, 1), a2 + hstep);
;       G8_WAIT_L(8); G8_BAR; G8_WAIT_L(0); G8_MMA(0, 0, At, B0); G8_BAR; G8_SCHED;
;       G8_LDB(B1, 1, 1); G8_STAGE(G8_SB(1, 0), b3);
;       G8_BAR; G8_WAIT_L(0); G8_MMA(0, 1, At, B1); G8_BAR;
;       G8_LDA(At, 1, 1); G8_STAGE(G8_SA(1, 0), a3);
;       G8_BAR; G8_WAIT_L(0); G8_MMA(1, 0, At, B0); G8_BAR; G8_SCHED;
;       G8_STAGE(G8_SB(1, 1), b3 + hstep);
;       G8_WAIT_V(6); G8_BAR; G8_MMA(1, 1, At, B1); G8_BAR;
	s_add_u32 s52, s20, 0x40000
	s_addc_u32 s53, s21, 0
	s_mov_b32 m0, s31
	v_lshl_add_u64 v[160:161], s[52:53], 0, v[132:133]
	global_load_lds_dwordx4 v[160:161], off
	v_lshl_add_u64 v[160:161], s[52:53], 0, v[130:131]
	s_mov_b32 m0, s34
	s_nop 0
	global_load_lds_dwordx4 v[160:161], off
	v_or_b32_e32 v159, 0x18000, v140
	v_add_u32_e32 v164, 0x18400, v140
	ds_read_b128 v[160:163], v159
	ds_read_b128 v[164:167], v164
	v_add_u32_e32 v159, 0x18800, v140
	v_add_u32_e32 v172, 0x18c00, v140
	ds_read_b128 v[168:171], v159
	ds_read_b128 v[172:175], v172
	s_waitcnt vmcnt(6)
	s_barrier
	s_setprio 1
	v_mfma_f32_16x16x32_f16 v[54:57], v[222:225], v[176:179], v[54:57]
	v_mfma_f32_16x16x32_f16 v[50:53], v[230:233], v[176:179], v[50:53]
	v_mfma_f32_16x16x32_f16 v[38:41], v[222:225], v[184:187], v[38:41]
	v_mfma_f32_16x16x32_f16 v[34:37], v[230:233], v[184:187], v[34:37]
	v_mfma_f32_16x16x32_f16 v[22:25], v[222:225], v[206:209], v[22:25]
	v_mfma_f32_16x16x32_f16 v[18:21], v[230:233], v[206:209], v[18:21]
	v_mfma_f32_16x16x32_f16 v[6:9], v[222:225], v[214:217], v[6:9]
	v_mfma_f32_16x16x32_f16 v[2:5], v[230:233], v[214:217], v[2:5]
	v_mfma_f32_16x16x32_f16 v[54:57], v[226:229], v[180:183], v[54:57]
	v_mfma_f32_16x16x32_f16 v[50:53], v[234:237], v[180:183], v[50:53]
	v_mfma_f32_16x16x32_f16 v[38:41], v[226:229], v[202:205], v[38:41]
	v_mfma_f32_16x16x32_f16 v[34:37], v[234:237], v[202:205], v[34:37]
	v_mfma_f32_16x16x32_f16 v[22:25], v[226:229], v[210:213], v[22:25]
	v_mfma_f32_16x16x32_f16 v[18:21], v[234:237], v[210:213], v[18:21]
	v_mfma_f32_16x16x32_f16 v[6:9], v[226:229], v[218:221], v[6:9]
	v_mfma_f32_16x16x32_f16 v[2:5], v[234:237], v[218:221], v[2:5]
	s_setprio 0
	s_barrier
	s_add_u32 s22, s22, 0x40000
	s_addc_u32 s23, s23, 0
	s_mov_b32 m0, s35
	v_lshl_add_u64 v[222:223], s[22:23], 0, v[132:133]
	ds_read_b128 v[176:179], v139 offset:32768
	ds_read_b128 v[180:183], v139 offset:33792
	ds_read_b128 v[184:187], v139 offset:34816
	ds_read_b128 v[202:205], v139 offset:35840
	ds_read_b128 v[206:209], v139 offset:36864
	ds_read_b128 v[210:213], v139 offset:37888
	ds_read_b128 v[214:217], v139 offset:38912
	ds_read_b128 v[218:221], v139 offset:39936
	global_load_lds_dwordx4 v[222:223], off
	s_waitcnt lgkmcnt(8)
	s_barrier
	s_waitcnt lgkmcnt(0)
	s_setprio 1
	s_waitcnt lgkmcnt(0)
	v_mfma_f32_16x16x32_f16 v[126:129], v[160:163], v[176:179], v[126:129]
	v_mfma_f32_16x16x32_f16 v[122:125], v[168:171], v[176:179], v[122:125]
	v_mfma_f32_16x16x32_f16 v[110:113], v[160:163], v[184:187], v[110:113]
	v_mfma_f32_16x16x32_f16 v[106:109], v[168:171], v[184:187], v[106:109]
	v_mfma_f32_16x16x32_f16 v[94:97], v[160:163], v[206:209], v[94:97]
	v_mfma_f32_16x16x32_f16 v[90:93], v[168:171], v[206:209], v[90:93]
	v_mfma_f32_16x16x32_f16 v[78:81], v[160:163], v[214:217], v[78:81]
	v_mfma_f32_16x16x32_f16 v[74:77], v[168:171], v[214:217], v[74:77]
	v_lshl_add_u64 v[222:223], s[22:23], 0, v[130:131]
	s_mov_b32 m0, s36
	s_nop 0
	global_load_lds_dwordx4 v[222:223], off
	v_mfma_f32_16x16x32_f16 v[126:129], v[164:167], v[180:183], v[126:129]
	v_mfma_f32_16x16x32_f16 v[122:125], v[172:175], v[180:183], v[122:125]
	v_mfma_f32_16x16x32_f16 v[110:113], v[164:167], v[202:205], v[110:113]
	v_mfma_f32_16x16x32_f16 v[106:109], v[172:175], v[202:205], v[106:109]
	v_mfma_f32_16x16x32_f16 v[94:97], v[164:167], v[210:213], v[94:97]
	v_mfma_f32_16x16x32_f16 v[90:93], v[172:175], v[210:213], v[90:93]
	v_mfma_f32_16x16x32_f16 v[78:81], v[164:167], v[218:221], v[78:81]
	v_mfma_f32_16x16x32_f16 v[74:77], v[172:175], v[218:221], v[74:77]
	s_setprio 0
	s_barrier
	v_or_b32_e32 v159, 0x1c000, v140
	s_mov_b32 m0, s37
	v_add_u32_e32 v195, 0x1c400, v140
	ds_read_b128 v[222:225], v159
	ds_read_b128 v[226:229], v195
	v_add_u32_e32 v159, 0x1c800, v140
	v_lshl_add_u64 v[188:189], v[188:189], 0, s[94:95]
	v_add_u32_e32 v195, 0x1cc00, v140
	ds_read_b128 v[230:233], v159
	ds_read_b128 v[234:237], v195
	global_load_lds_dwordx4 v[188:189], off
	s_barrier
	s_waitcnt lgkmcnt(0)
	s_setprio 1
	s_waitcnt lgkmcnt(0)
	v_mfma_f32_16x16x32_f16 v[118:121], v[222:225], v[176:179], v[118:121]
	v_mfma_f32_16x16x32_f16 v[114:117], v[230:233], v[176:179], v[114:117]
	v_mfma_f32_16x16x32_f16 v[102:105], v[222:225], v[184:187], v[102:105]
	v_mfma_f32_16x16x32_f16 v[98:101], v[230:233], v[184:187], v[98:101]
	v_mfma_f32_16x16x32_f16 v[86:89], v[222:225], v[206:209], v[86:89]
	v_mfma_f32_16x16x32_f16 v[82:85], v[230:233], v[206:209], v[82:85]
	v_mfma_f32_16x16x32_f16 v[70:73], v[222:225], v[214:217], v[70:73]
	v_mfma_f32_16x16x32_f16 v[66:69], v[230:233], v[214:217], v[66:69]
	v_lshl_add_u64 v[188:189], v[238:239], 0, s[94:95]
	s_mov_b32 m0, s38
	s_nop 0
	global_load_lds_dwordx4 v[188:189], off
	v_mfma_f32_16x16x32_f16 v[118:121], v[226:229], v[180:183], v[118:121]
	v_mfma_f32_16x16x32_f16 v[114:117], v[234:237], v[180:183], v[114:117]
	v_mfma_f32_16x16x32_f16 v[102:105], v[226:229], v[202:205], v[102:105]
	v_mfma_f32_16x16x32_f16 v[98:101], v[234:237], v[202:205], v[98:101]
	v_mfma_f32_16x16x32_f16 v[86:89], v[226:229], v[210:213], v[86:89]
	v_mfma_f32_16x16x32_f16 v[82:85], v[234:237], v[210:213], v[82:85]
	v_mfma_f32_16x16x32_f16 v[70:73], v[226:229], v[218:221], v[70:73]
	v_mfma_f32_16x16x32_f16 v[66:69], v[234:237], v[218:221], v[66:69]
	s_setprio 0
	s_mov_b32 m0, s39
	v_lshl_add_u64 v[188:189], v[240:241], 0, s[94:95]
	s_barrier
	ds_read_b128 v[176:179], v139 offset:49152
	ds_read_b128 v[180:183], v139 offset:50176
	ds_read_b128 v[184:187], v139 offset:51200
	ds_read_b128 v[202:205], v139 offset:52224
	ds_read_b128 v[206:209], v139 offset:53248
	ds_read_b128 v[210:213], v139 offset:54272
	ds_read_b128 v[214:217], v139 offset:55296
	ds_read_b128 v[218:221], v139 offset:56320
	global_load_lds_dwordx4 v[188:189], off
	s_waitcnt vmcnt(9)
	s_barrier
; #define G8_STAGE(bufoff, gbase) do { _Pragma("unroll") for (int _i = 0; _i < 2; ++_i) \
;     __builtin_amdgcn_global_load_lds((const unsigned*)((const char*)(gbase) + voffA[_i]), (LAS unsigned*)(lds + (bufoff) + ldsw + _i * 8192), 16, 0, 0); } while (0)
; #define G8_LDA(dst, b, h) do { _Pragma("unroll") for (int m = 0; m < 4; ++m) _Pragma("unroll") for (int k = 0; k < 2; ++k) dst[m][k] = *(const LAS h16x8*)(lds + G8_SA(b, h) + aoff + m * 2048 + k * 1024); } while (0)
; #define G8_LDB(dst, b, h) do { _Pragma("unroll") for (int n = 0; n < 2; ++n) _Pragma("unroll") for (int k = 0; k < 2; ++k) dst[n][k] = *(const LAS h16x8*)(lds + G8_SB(b, h) + boff + n * 2048 + k * 1024); } while (0)
; #define G8_WAIT_V(n) asm volatile("s_waitcnt vmcnt(" #n ")" ::: "memory")
; #define G8_WAIT_L(n) asm volatile("s_waitcnt lgkmcnt(" #n ")" ::: "memory")
; #define G8_BAR __builtin_amdgcn_s_barrier()
; #define G8_SCHED __builtin_amdgcn_sched_barrier(0)
; template <class Epi>
; __device__ __forceinline__ void gemm_phase(LAS unsigned char* lds, const h16* A, const h16* Bt, int K, const Order& S, const Epi& E) {
;     ...
;       G8_LDB(B1, 1, 1); G8_STAGE(G8_SB(1, 0), b3);
;       G8_BAR; G8_WAIT_L(0); G8_MMA(0, 1, At, B1); G8_BAR;
;       G8_LDA(At, 1, 1); G8_STAGE(G8_SA(1, 0), a3);
;       G8_BAR; G8_WAIT_L(0); G8_MMA(1, 0, At, B0); G8_BAR; G8_SCHED;
;       G8_STAGE(G8_SB(1, 1), b3 + hstep);
;       G8_WAIT_V(6); G8_BAR; G8_MMA(1, 1, At, B1); G8_BAR;
;   __device__ __forceinline__ void operator()(const f32x4 (&acc)[2][2][4][2], const g8::Unit& u, int ui, int wr, int wc, int fr, int fq) const {
; #pragma unroll
;     for (int ai = 0; ai < 2; ++ai)
; #pragma unroll
;       for (int m = 0; m < 4; ++m) {
;         const int rl = 128 * ai + 64 * wr + 16 * m + fr;
;         const float r = rsl[ui * 256 + rl];
;         h16* rowp = hid + (size_t)(u.pm * 256 + rl) * DFF + 256 * u.pn + 32 * wc + 8 * fq;
; #pragma unroll
;         for (int bj = 0; bj < 2; ++bj) {
;           f32x4 v[2];
; #pragma unroll
;           for (int n = 0; n < 2; ++n) {
;             v[n] = acc[ai][bj][m][n] * r;
; #pragma unroll
;             for (int j = 0; j < 4; ++j) { const float t = fmaxf(v[n][j], 0.f); v[n][j] = t * t; }
;           }
;           __builtin_nontemporal_store(pack8(v[0], v[1]), (h16x8*)(rowp + 128 * bj));
;         }
	s_waitcnt lgkmcnt(0)
	s_setprio 1
	s_waitcnt lgkmcnt(0)
	v_mfma_f32_16x16x32_f16 v[62:65], v[160:163], v[176:179], v[62:65]
	v_mfma_f32_16x16x32_f16 v[58:61], v[168:171], v[176:179], v[58:61]
	v_mfma_f32_16x16x32_f16 v[46:49], v[160:163], v[184:187], v[46:49]
	v_mfma_f32_16x16x32_f16 v[42:45], v[168:171], v[184:187], v[42:45]
	v_mfma_f32_16x16x32_f16 v[30:33], v[160:163], v[206:209], v[30:33]
	v_mfma_f32_16x16x32_f16 v[26:29], v[168:171], v[206:209], v[26:29]
	v_mfma_f32_16x16x32_f16 v[14:17], v[160:163], v[214:217], v[14:17]
	v_mfma_f32_16x16x32_f16 v[10:13], v[168:171], v[214:217], v[10:13]
	v_lshl_add_u64 v[188:189], v[242:243], 0, s[94:95]
	s_mov_b32 m0, s40
	s_nop 0
	global_load_lds_dwordx4 v[188:189], off
	v_mfma_f32_16x16x32_f16 v[62:65], v[164:167], v[180:183], v[62:65]
	v_mfma_f32_16x16x32_f16 v[58:61], v[172:175], v[180:183], v[58:61]
	v_mfma_f32_16x16x32_f16 v[46:49], v[164:167], v[202:205], v[46:49]
	v_mfma_f32_16x16x32_f16 v[42:45], v[172:175], v[202:205], v[42:45]
	v_mfma_f32_16x16x32_f16 v[30:33], v[164:167], v[210:213], v[30:33]
	v_mfma_f32_16x16x32_f16 v[26:29], v[172:175], v[210:213], v[26:29]
	v_mfma_f32_16x16x32_f16 v[14:17], v[164:167], v[218:221], v[14:17]
	v_mfma_f32_16x16x32_f16 v[10:13], v[172:175], v[218:221], v[10:13]
	s_setprio 0
	s_barrier
	s_add_u32 s20, s20, 0x40080
	s_addc_u32 s21, s21, 0
	s_mov_b32 m0, s41
	v_lshl_add_u64 v[160:161], s[20:21], 0, v[132:133]
	global_load_lds_dwordx4 v[160:161], off
	v_lshl_add_u64 v[160:161], s[20:21], 0, v[130:131]
	s_mov_b32 m0, s42
	s_nop 0
	global_load_lds_dwordx4 v[160:161], off
	v_or_b32_e32 v159, 0x10000, v140
	v_add_u32_e32 v164, 0x10400, v140
	ds_read_b128 v[160:163], v159
	ds_read_b128 v[164:167], v164
	v_add_u32_e32 v159, 0x10800, v140
	v_add_u32_e32 v172, 0x10c00, v140
	ds_read_b128 v[168:171], v159
	ds_read_b128 v[172:175], v172
	s_waitcnt vmcnt(6)
	s_barrier
	s_setprio 1
	v_mfma_f32_16x16x32_f16 v[54:57], v[222:225], v[176:179], v[54:57]
	v_mfma_f32_16x16x32_f16 v[50:53], v[230:233], v[176:179], v[50:53]
	v_mfma_f32_16x16x32_f16 v[38:41], v[222:225], v[184:187], v[38:41]
	v_mfma_f32_16x16x32_f16 v[34:37], v[230:233], v[184:187], v[34:37]
	v_mfma_f32_16x16x32_f16 v[22:25], v[222:225], v[206:209], v[22:25]
	v_mfma_f32_16x16x32_f16 v[18:21], v[230:233], v[206:209], v[18:21]
	v_mfma_f32_16x16x32_f16 v[6:9], v[222:225], v[214:217], v[6:9]
	v_mfma_f32_16x16x32_f16 v[2:5], v[230:233], v[214:217], v[2:5]
	v_mfma_f32_16x16x32_f16 v[54:57], v[226:229], v[180:183], v[54:57]
	v_mfma_f32_16x16x32_f16 v[50:53], v[234:237], v[180:183], v[50:53]
	v_mfma_f32_16x16x32_f16 v[38:41], v[226:229], v[202:205], v[38:41]
	v_mfma_f32_16x16x32_f16 v[34:37], v[234:237], v[202:205], v[34:37]
	v_mfma_f32_16x16x32_f16 v[22:25], v[226:229], v[210:213], v[22:25]
	v_mfma_f32_16x16x32_f16 v[18:21], v[234:237], v[210:213], v[18:21]
	v_mfma_f32_16x16x32_f16 v[6:9], v[226:229], v[218:221], v[6:9]
	v_mfma_f32_16x16x32_f16 v[2:5], v[234:237], v[218:221], v[2:5]
	s_setprio 0
	s_add_i32 s51, s51, 2
	s_add_u32 s18, s18, 0x100
	s_addc_u32 s19, s19, 0
	s_add_u32 s49, s49, 0x100
	s_addc_u32 s50, s50, 0
	s_cmp_gt_u32 s51, 13
	s_barrier
	s_cbranch_scc0 .LBB0_2473
	s_waitcnt lgkmcnt(0)
	v_lshl_add_u32 v159, s44, 10, v158
	s_waitcnt vmcnt(0)
	ds_read2_b32 v[160:161], v159 offset1:16
	s_lshl_b32 s11, s46, 8
	v_add_u32_e32 v162, s11, v138
	s_lshl_b32 s18, s45, 8
	v_ashrrev_i32_e32 v163, 31, v162
	s_waitcnt lgkmcnt(0)
	v_pk_mul_f32 v[128:129], v[128:129], v[160:161] op_sel_hi:[1,0]
	v_pk_mul_f32 v[126:127], v[126:127], v[160:161] op_sel_hi:[1,0]
	v_pk_mul_f32 v[122:123], v[122:123], v[160:161] op_sel_hi:[1,0]
	v_max_f32_e32 v166, 0, v126
	v_max_f32_e32 v126, 0, v127
	v_max_f32_e32 v127, 0, v128
	v_max_f32_e32 v128, 0, v129
	v_pk_mul_f32 v[124:125], v[124:125], v[160:161] op_sel_hi:[1,0]
	v_max_f32_e32 v129, 0, v122
	v_max_f32_e32 v164, 0, v123
	v_pk_mul_f32 v[122:123], v[126:127], v[126:127]
	v_max_f32_e32 v165, 0, v124
	v_fma_mixlo_f16 v124, v166, v166, 0
	v_cvt_pk_f16_f32 v123, v122, v123
	s_ashr_i32 s19, s18, 31
	v_lshlrev_b64 v[162:163], 13, v[162:163]
	v_max_f32_e32 v167, 0, v125
	v_pack_b32_f16 v122, v124, v123
	v_pk_mul_f32 v[124:125], v[128:129], v[128:129]
	v_lshl_add_u64 v[162:163], s[0:1], 0, v[162:163]
	s_lshl_b64 s[18:19], s[18:19], 1
	v_cvt_pk_f16_f32 v126, v124, v125
	v_pk_mul_f32 v[124:125], v[164:165], v[164:165]
	v_lshl_add_u64 v[162:163], v[162:163], 0, s[18:19]
	v_cvt_pk_f16_f32 v125, v124, v125
	v_lshl_add_u64 v[162:163], v[162:163], 0, s[92:93]
	v_alignbit_b32 v124, v125, v126, 16
	v_lshrrev_b32_e32 v125, 16, v125
	v_lshl_add_u64 v[162:163], v[162:163], 0, v[0:1]
	v_alignbit_b32 v123, v126, v123, 16
	v_fma_mixhi_f16 v125, v167, v167, 0
	v_pk_mul_f32 v[120:121], v[120:121], v[160:161] op_sel_hi:[1,0]
	v_pk_mul_f32 v[118:119], v[118:119], v[160:161] op_sel_hi:[1,0]
	global_store_dwordx4 v[162:163], v[122:125], off nt
	v_pk_mul_f32 v[114:115], v[114:115], v[160:161] op_sel_hi:[1,0]
	v_pk_mul_f32 v[116:117], v[116:117], v[160:161] op_sel_hi:[1,0]
	v_max_f32_e32 v124, 0, v118
	v_max_f32_e32 v118, 0, v119
	v_max_f32_e32 v119, 0, v120
	v_max_f32_e32 v120, 0, v121
	v_max_f32_e32 v121, 0, v114
	v_max_f32_e32 v122, 0, v115
	v_pk_mul_f32 v[114:115], v[118:119], v[118:119]
	v_max_f32_e32 v123, 0, v116
	v_fma_mixlo_f16 v116, v124, v124, 0
	v_cvt_pk_f16_f32 v115, v114, v115
	v_max_f32_e32 v125, 0, v117
	v_pack_b32_f16 v114, v116, v115
	v_pk_mul_f32 v[116:117], v[120:121], v[120:121]
	s_and_b64 vcc, exec, s[6:7]
	v_cvt_pk_f16_f32 v118, v116, v117
	v_pk_mul_f32 v[116:117], v[122:123], v[122:123]
	v_alignbit_b32 v115, v118, v115, 16
	v_cvt_pk_f16_f32 v117, v116, v117
	v_alignbit_b32 v116, v117, v118, 16
;   __device__ __forceinline__ void operator()(const f32x4 (&acc)[2][2][4][2], const g8::Unit& u, int ui, int wr, int wc, int fr, int fq) const {
; #pragma unroll
;     for (int ai = 0; ai < 2; ++ai)
; #pragma unroll
;       for (int m = 0; m < 4; ++m) {
;         const int rl = 128 * ai + 64 * wr + 16 * m + fr;
;         const float r = rsl[ui * 256 + rl];
;         h16* rowp = hid + (size_t)(u.pm * 256 + rl) * DFF + 256 * u.pn + 32 * wc + 8 * fq;
; #pragma unroll
;         for (int bj = 0; bj < 2; ++bj) {
;           f32x4 v[2];
; #pragma unroll
;           for (int n = 0; n < 2; ++n) {
;             v[n] = acc[ai][bj][m][n] * r;
; #pragma unroll
;             for (int j = 0; j < 4; ++j) { const float t = fmaxf(v[n][j], 0.f); v[n][j] = t * t; }
;           }
;           __builtin_nontemporal_store(pack8(v[0], v[1]), (h16x8*)(rowp + 128 * bj));
;         }
	v_lshrrev_b32_e32 v117, 16, v117
	v_fma_mixhi_f16 v117, v125, v125, 0
	global_store_dwordx4 v[162:163], v[114:117], off offset:256 nt
	s_mov_b32 s45, s10
	s_mov_b32 s46, s12
	v_mov_b32_e32 v116, v161
	v_pk_mul_f32 v[110:111], v[110:111], v[116:117] op_sel_hi:[1,0]
	v_pk_mul_f32 v[112:113], v[112:113], v[116:117] op_sel_hi:[1,0]
	v_max_f32_e32 v117, 0, v110
	v_max_f32_e32 v110, 0, v111
	v_max_f32_e32 v111, 0, v112
	v_pk_mul_f32 v[106:107], v[106:107], v[116:117] op_sel_hi:[1,0]
	v_add_u32_e32 v114, s11, v141
	v_max_f32_e32 v112, 0, v113
	v_pk_mul_f32 v[108:109], v[108:109], v[116:117] op_sel_hi:[1,0]
	v_max_f32_e32 v113, 0, v106
	v_max_f32_e32 v118, 0, v107
	v_pk_mul_f32 v[106:107], v[110:111], v[110:111]
	v_ashrrev_i32_e32 v115, 31, v114
	v_max_f32_e32 v119, 0, v108
	v_fma_mixlo_f16 v108, v117, v117, 0
	v_cvt_pk_f16_f32 v107, v106, v107
	v_lshlrev_b64 v[114:115], 13, v[114:115]
	v_max_f32_e32 v120, 0, v109
	v_pack_b32_f16 v106, v108, v107
	v_pk_mul_f32 v[108:109], v[112:113], v[112:113]
	v_lshl_add_u64 v[114:115], s[0:1], 0, v[114:115]
	v_cvt_pk_f16_f32 v110, v108, v109
	v_pk_mul_f32 v[108:109], v[118:119], v[118:119]
	v_lshl_add_u64 v[114:115], v[114:115], 0, s[18:19]
	v_cvt_pk_f16_f32 v109, v108, v109
	v_lshl_add_u64 v[114:115], v[114:115], 0, s[92:93]
	v_alignbit_b32 v108, v109, v110, 16
	v_lshrrev_b32_e32 v109, 16, v109
	v_lshl_add_u64 v[114:115], v[114:115], 0, v[0:1]
	v_alignbit_b32 v107, v110, v107, 16
	v_fma_mixhi_f16 v109, v120, v120, 0
	v_pk_mul_f32 v[104:105], v[104:105], v[116:117] op_sel_hi:[1,0]
	v_pk_mul_f32 v[102:103], v[102:103], v[116:117] op_sel_hi:[1,0]
	global_store_dwordx4 v[114:115], v[106:109], off nt
	v_pk_mul_f32 v[98:99], v[98:99], v[116:117] op_sel_hi:[1,0]
	v_pk_mul_f32 v[100:101], v[100:101], v[116:117] op_sel_hi:[1,0]
	v_max_f32_e32 v108, 0, v102
	v_max_f32_e32 v102, 0, v103
	v_max_f32_e32 v103, 0, v104
	v_max_f32_e32 v104, 0, v105
	v_max_f32_e32 v105, 0, v98
	v_max_f32_e32 v106, 0, v99
	v_pk_mul_f32 v[98:99], v[102:103], v[102:103]
	v_max_f32_e32 v107, 0, v100
	v_fma_mixlo_f16 v100, v108, v108, 0
	v_cvt_pk_f16_f32 v99, v98, v99
	v_max_f32_e32 v109, 0, v101
	v_pack_b32_f16 v98, v100, v99
	v_pk_mul_f32 v[100:101], v[104:105], v[104:105]
	s_mov_b64 s[20:21], s[16:17]
	v_cvt_pk_f16_f32 v102, v100, v101
	v_pk_mul_f32 v[100:101], v[106:107], v[106:107]
	v_alignbit_b32 v99, v102, v99, 16
	v_cvt_pk_f16_f32 v101, v100, v101
	v_alignbit_b32 v100, v101, v102, 16
	v_lshrrev_b32_e32 v101, 16, v101
	v_fma_mixhi_f16 v101, v109, v109, 0
	global_store_dwordx4 v[114:115], v[98:101], off offset:256 nt
	ds_read2_b32 v[98:99], v159 offset0:32 offset1:48
	s_mov_b32 s44, s43
	v_add_u32_e32 v100, s11, v152
	v_ashrrev_i32_e32 v101, 31, v100
	v_lshlrev_b64 v[100:101], 13, v[100:101]
	s_waitcnt lgkmcnt(0)
	v_pk_mul_f32 v[96:97], v[96:97], v[98:99] op_sel_hi:[1,0]
	v_pk_mul_f32 v[94:95], v[94:95], v[98:99] op_sel_hi:[1,0]
	v_pk_mul_f32 v[90:91], v[90:91], v[98:99] op_sel_hi:[1,0]
	v_max_f32_e32 v104, 0, v94
	v_max_f32_e32 v94, 0, v95
	v_max_f32_e32 v95, 0, v96
	v_max_f32_e32 v96, 0, v97
	v_pk_mul_f32 v[92:93], v[92:93], v[98:99] op_sel_hi:[1,0]
	v_max_f32_e32 v97, 0, v90
	v_max_f32_e32 v102, 0, v91
	v_pk_mul_f32 v[90:91], v[94:95], v[94:95]
	v_max_f32_e32 v103, 0, v92
	v_fma_mixlo_f16 v92, v104, v104, 0
	v_cvt_pk_f16_f32 v91, v90, v91
	v_max_f32_e32 v105, 0, v93
	v_pack_b32_f16 v90, v92, v91
	v_pk_mul_f32 v[92:93], v[96:97], v[96:97]
	v_lshl_add_u64 v[100:101], s[0:1], 0, v[100:101]
	v_cvt_pk_f16_f32 v94, v92, v93
	v_pk_mul_f32 v[92:93], v[102:103], v[102:103]
	v_lshl_add_u64 v[100:101], v[100:101], 0, s[18:19]
	v_cvt_pk_f16_f32 v93, v92, v93
	v_lshl_add_u64 v[100:101], v[100:101], 0, s[92:93]
	v_alignbit_b32 v92, v93, v94, 16
	v_lshrrev_b32_e32 v93, 16, v93
	v_lshl_add_u64 v[100:101], v[100:101], 0, v[0:1]
	v_alignbit_b32 v91, v94, v91, 16
	v_fma_mixhi_f16 v93, v105, v105, 0
	v_pk_mul_f32 v[88:89], v[88:89], v[98:99] op_sel_hi:[1,0]
	v_pk_mul_f32 v[86:87], v[86:87], v[98:99] op_sel_hi:[1,0]
	global_store_dwordx4 v[100:101], v[90:93], off nt
	v_pk_mul_f32 v[82:83], v[82:83], v[98:99] op_sel_hi:[1,0]
	v_pk_mul_f32 v[84:85], v[84:85], v[98:99] op_sel_hi:[1,0]
	v_max_f32_e32 v92, 0, v86
	v_max_f32_e32 v86, 0, v87
	v_max_f32_e32 v87, 0, v88
	v_max_f32_e32 v88, 0, v89
	v_max_f32_e32 v89, 0, v82
	v_max_f32_e32 v90, 0, v83
	v_pk_mul_f32 v[82:83], v[86:87], v[86:87]
	v_max_f32_e32 v91, 0, v84
	v_fma_mixlo_f16 v84, v92, v92, 0
	v_cvt_pk_f16_f32 v83, v82, v83
	v_max_f32_e32 v93, 0, v85
	v_pack_b32_f16 v82, v84, v83
	v_pk_mul_f32 v[84:85], v[88:89], v[88:89]
	s_nop 0
	v_cvt_pk_f16_f32 v86, v84, v85
	v_pk_mul_f32 v[84:85], v[90:91], v[90:91]
	v_alignbit_b32 v83, v86, v83, 16
	v_cvt_pk_f16_f32 v85, v84, v85
	v_alignbit_b32 v84, v85, v86, 16
	v_lshrrev_b32_e32 v85, 16, v85
	v_fma_mixhi_f16 v85, v93, v93, 0
	global_store_dwordx4 v[100:101], v[82:85], off offset:256 nt
	s_nop 1
	v_mov_b32_e32 v84, v99
	v_pk_mul_f32 v[78:79], v[78:79], v[84:85] op_sel_hi:[1,0]
	v_pk_mul_f32 v[80:81], v[80:81], v[84:85] op_sel_hi:[1,0]
	v_max_f32_e32 v85, 0, v78
	v_max_f32_e32 v78, 0, v79
	v_max_f32_e32 v79, 0, v80
	v_pk_mul_f32 v[74:75], v[74:75], v[84:85] op_sel_hi:[1,0]
	v_add_u32_e32 v82, s11, v153
	v_max_f32_e32 v80, 0, v81
	v_pk_mul_f32 v[76:77], v[76:77], v[84:85] op_sel_hi:[1,0]
	v_max_f32_e32 v81, 0, v74
	v_max_f32_e32 v86, 0, v75
	v_pk_mul_f32 v[74:75], v[78:79], v[78:79]
	v_ashrrev_i32_e32 v83, 31, v82
	v_max_f32_e32 v87, 0, v76
	v_fma_mixlo_f16 v76, v85, v85, 0
	v_cvt_pk_f16_f32 v75, v74, v75
	v_lshlrev_b64 v[82:83], 13, v[82:83]
	v_max_f32_e32 v88, 0, v77
	v_pack_b32_f16 v74, v76, v75
	v_pk_mul_f32 v[76:77], v[80:81], v[80:81]
	v_lshl_add_u64 v[82:83], s[0:1], 0, v[82:83]
;   __device__ __forceinline__ void operator()(const f32x4 (&acc)[2][2][4][2], const g8::Unit& u, int ui, int wr, int wc, int fr, int fq) const {
; #pragma unroll
;     for (int ai = 0; ai < 2; ++ai)
; #pragma unroll
;       for (int m = 0; m < 4; ++m) {
;         const int rl = 128 * ai + 64 * wr + 16 * m + fr;
;         const float r = rsl[ui * 256 + rl];
;         h16* rowp = hid + (size_t)(u.pm * 256 + rl) * DFF + 256 * u.pn + 32 * wc + 8 * fq;
; #pragma unroll
;         for (int bj = 0; bj < 2; ++bj) {
;           f32x4 v[2];
; #pragma unroll
;           for (int n = 0; n < 2; ++n) {
;             v[n] = acc[ai][bj][m][n] * r;
; #pragma unroll
;             for (int j = 0; j < 4; ++j) { const float t = fmaxf(v[n][j], 0.f); v[n][j] = t * t; }
;           }
;           __builtin_nontemporal_store(pack8(v[0], v[1]), (h16x8*)(rowp + 128 * bj));
;         }
	v_cvt_pk_f16_f32 v78, v76, v77
	v_pk_mul_f32 v[76:77], v[86:87], v[86:87]
	v_lshl_add_u64 v[82:83], v[82:83], 0, s[18:19]
	v_cvt_pk_f16_f32 v77, v76, v77
	v_lshl_add_u64 v[82:83], v[82:83], 0, s[92:93]
	v_alignbit_b32 v76, v77, v78, 16
	v_lshrrev_b32_e32 v77, 16, v77
	v_lshl_add_u64 v[82:83], v[82:83], 0, v[0:1]
	v_alignbit_b32 v75, v78, v75, 16
	v_fma_mixhi_f16 v77, v88, v88, 0
	v_pk_mul_f32 v[72:73], v[72:73], v[84:85] op_sel_hi:[1,0]
	v_pk_mul_f32 v[70:71], v[70:71], v[84:85] op_sel_hi:[1,0]
	global_store_dwordx4 v[82:83], v[74:77], off nt
	v_pk_mul_f32 v[66:67], v[66:67], v[84:85] op_sel_hi:[1,0]
	v_pk_mul_f32 v[68:69], v[68:69], v[84:85] op_sel_hi:[1,0]
	v_max_f32_e32 v76, 0, v70
	v_max_f32_e32 v70, 0, v71
	v_max_f32_e32 v71, 0, v72
	v_max_f32_e32 v72, 0, v73
	v_max_f32_e32 v73, 0, v66
	v_max_f32_e32 v74, 0, v67
	v_pk_mul_f32 v[66:67], v[70:71], v[70:71]
	v_max_f32_e32 v75, 0, v68
	v_fma_mixlo_f16 v68, v76, v76, 0
	v_cvt_pk_f16_f32 v67, v66, v67
	v_max_f32_e32 v77, 0, v69
	v_pack_b32_f16 v66, v68, v67
	v_pk_mul_f32 v[68:69], v[72:73], v[72:73]
	s_nop 0
	v_cvt_pk_f16_f32 v70, v68, v69
	v_pk_mul_f32 v[68:69], v[74:75], v[74:75]
	v_alignbit_b32 v67, v70, v67, 16
	v_cvt_pk_f16_f32 v69, v68, v69
	v_alignbit_b32 v68, v69, v70, 16
	v_lshrrev_b32_e32 v69, 16, v69
	v_fma_mixhi_f16 v69, v77, v77, 0
	global_store_dwordx4 v[82:83], v[66:69], off offset:256 nt
	ds_read2_b32 v[66:67], v159 offset0:128 offset1:144
	s_waitcnt lgkmcnt(0)
	v_pk_mul_f32 v[64:65], v[64:65], v[66:67] op_sel_hi:[1,0]
	v_pk_mul_f32 v[62:63], v[62:63], v[66:67] op_sel_hi:[1,0]
	v_pk_mul_f32 v[58:59], v[58:59], v[66:67] op_sel_hi:[1,0]
	v_max_f32_e32 v72, 0, v62
	v_max_f32_e32 v62, 0, v63
	v_max_f32_e32 v63, 0, v64
	v_add_u32_e32 v68, s11, v154
	v_max_f32_e32 v64, 0, v65
	v_pk_mul_f32 v[60:61], v[60:61], v[66:67] op_sel_hi:[1,0]
	v_max_f32_e32 v65, 0, v58
	v_max_f32_e32 v70, 0, v59
	v_pk_mul_f32 v[58:59], v[62:63], v[62:63]
	v_ashrrev_i32_e32 v69, 31, v68
	v_max_f32_e32 v71, 0, v60
	v_fma_mixlo_f16 v60, v72, v72, 0
	v_cvt_pk_f16_f32 v59, v58, v59
	v_lshlrev_b64 v[68:69], 13, v[68:69]
	v_max_f32_e32 v73, 0, v61
	v_pack_b32_f16 v58, v60, v59
	v_pk_mul_f32 v[60:61], v[64:65], v[64:65]
	v_lshl_add_u64 v[68:69], s[0:1], 0, v[68:69]
	v_cvt_pk_f16_f32 v62, v60, v61
	v_pk_mul_f32 v[60:61], v[70:71], v[70:71]
	v_lshl_add_u64 v[68:69], v[68:69], 0, s[18:19]
	v_cvt_pk_f16_f32 v61, v60, v61
	v_lshl_add_u64 v[68:69], v[68:69], 0, s[92:93]
	v_alignbit_b32 v60, v61, v62, 16
	v_lshrrev_b32_e32 v61, 16, v61
	v_lshl_add_u64 v[68:69], v[68:69], 0, v[0:1]
	v_alignbit_b32 v59, v62, v59, 16
	v_fma_mixhi_f16 v61, v73, v73, 0
	v_pk_mul_f32 v[56:57], v[56:57], v[66:67] op_sel_hi:[1,0]
	v_pk_mul_f32 v[54:55], v[54:55], v[66:67] op_sel_hi:[1,0]
	global_store_dwordx4 v[68:69], v[58:61], off nt
	v_pk_mul_f32 v[50:51], v[50:51], v[66:67] op_sel_hi:[1,0]
	v_pk_mul_f32 v[52:53], v[52:53], v[66:67] op_sel_hi:[1,0]
	v_max_f32_e32 v60, 0, v54
	v_max_f32_e32 v54, 0, v55
	v_max_f32_e32 v55, 0, v56
	v_max_f32_e32 v56, 0, v57
	v_max_f32_e32 v57, 0, v50
	v_max_f32_e32 v58, 0, v51
	v_pk_mul_f32 v[50:51], v[54:55], v[54:55]
	v_max_f32_e32 v59, 0, v52
	v_fma_mixlo_f16 v52, v60, v60, 0
	v_cvt_pk_f16_f32 v51, v50, v51
	v_max_f32_e32 v61, 0, v53
	v_pack_b32_f16 v50, v52, v51
	v_pk_mul_f32 v[52:53], v[56:57], v[56:57]
	s_nop 0
	v_cvt_pk_f16_f32 v54, v52, v53
	v_pk_mul_f32 v[52:53], v[58:59], v[58:59]
	v_alignbit_b32 v51, v54, v51, 16
	v_cvt_pk_f16_f32 v53, v52, v53
	v_alignbit_b32 v52, v53, v54, 16
	v_lshrrev_b32_e32 v53, 16, v53
	v_fma_mixhi_f16 v53, v61, v61, 0
	global_store_dwordx4 v[68:69], v[50:53], off offset:256 nt
	s_nop 1
	v_mov_b32_e32 v52, v67
	v_pk_mul_f32 v[46:47], v[46:47], v[52:53] op_sel_hi:[1,0]
	v_pk_mul_f32 v[48:49], v[48:49], v[52:53] op_sel_hi:[1,0]
	v_max_f32_e32 v53, 0, v46
	v_max_f32_e32 v46, 0, v47
	v_max_f32_e32 v47, 0, v48
	v_pk_mul_f32 v[42:43], v[42:43], v[52:53] op_sel_hi:[1,0]
	v_add_u32_e32 v50, s11, v155
	v_max_f32_e32 v48, 0, v49
	v_pk_mul_f32 v[44:45], v[44:45], v[52:53] op_sel_hi:[1,0]
	v_max_f32_e32 v49, 0, v42
	v_max_f32_e32 v54, 0, v43
	v_pk_mul_f32 v[42:43], v[46:47], v[46:47]
	v_ashrrev_i32_e32 v51, 31, v50
	v_max_f32_e32 v55, 0, v44
	v_fma_mixlo_f16 v44, v53, v53, 0
	v_cvt_pk_f16_f32 v43, v42, v43
	v_lshlrev_b64 v[50:51], 13, v[50:51]
	v_max_f32_e32 v56, 0, v45
	v_pack_b32_f16 v42, v44, v43
	v_pk_mul_f32 v[44:45], v[48:49], v[48:49]
	v_lshl_add_u64 v[50:51], s[0:1], 0, v[50:51]
	v_cvt_pk_f16_f32 v46, v44, v45
	v_pk_mul_f32 v[44:45], v[54:55], v[54:55]
	v_lshl_add_u64 v[50:51], v[50:51], 0, s[18:19]
	v_cvt_pk_f16_f32 v45, v44, v45
	v_lshl_add_u64 v[50:51], v[50:51], 0, s[92:93]
	v_alignbit_b32 v44, v45, v46, 16
	v_lshrrev_b32_e32 v45, 16, v45
	v_lshl_add_u64 v[50:51], v[50:51], 0, v[0:1]
	v_alignbit_b32 v43, v46, v43, 16
	v_fma_mixhi_f16 v45, v56, v56, 0
	v_pk_mul_f32 v[40:41], v[40:41], v[52:53] op_sel_hi:[1,0]
	v_pk_mul_f32 v[38:39], v[38:39], v[52:53] op_sel_hi:[1,0]
	global_store_dwordx4 v[50:51], v[42:45], off nt
	v_pk_mul_f32 v[34:35], v[34:35], v[52:53] op_sel_hi:[1,0]
	v_pk_mul_f32 v[36:37], v[36:37], v[52:53] op_sel_hi:[1,0]
	v_max_f32_e32 v44, 0, v38
	v_max_f32_e32 v38, 0, v39
	v_max_f32_e32 v39, 0, v40
	v_max_f32_e32 v40, 0, v41
	v_max_f32_e32 v41, 0, v34
	v_max_f32_e32 v42, 0, v35
	v_pk_mul_f32 v[34:35], v[38:39], v[38:39]
	v_max_f32_e32 v43, 0, v36
	v_fma_mixlo_f16 v36, v44, v44, 0
	v_cvt_pk_f16_f32 v35, v34, v35
	v_max_f32_e32 v45, 0, v37
	v_pack_b32_f16 v34, v36, v35
	v_pk_mul_f32 v[36:37], v[40:41], v[40:41]
	s_nop 0
	v_cvt_pk_f16_f32 v38, v36, v37
	v_pk_mul_f32 v[36:37], v[42:43], v[42:43]
	v_alignbit_b32 v35, v38, v35, 16
	v_cvt_pk_f16_f32 v37, v36, v37
	v_alignbit_b32 v36, v37, v38, 16
	v_lshrrev_b32_e32 v37, 16, v37
	v_fma_mixhi_f16 v37, v45, v45, 0
	global_store_dwordx4 v[50:51], v[34:37], off offset:256 nt
	ds_read2_b32 v[34:35], v159 offset0:160 offset1:176
	s_waitcnt lgkmcnt(0)
; #define G8_WAIT_V(n) asm volatile("s_waitcnt vmcnt(" #n ")" ::: "memory")
; #define G8_BAR __builtin_amdgcn_s_barrier()
; template <class Epi>
; __device__ __forceinline__ void gemm_phase(LAS unsigned char* lds, const h16* A, const h16* Bt, int K, const Order& S, const Epi& E) {
;     ...
;     if (!has_next) break;
; #pragma unroll
;     for (int a = 0; a < 2; ++a)
; #pragma unroll
;       for (int b = 0; b < 2; ++b)
; #pragma unroll
;         for (int m = 0; m < 4; ++m)
; #pragma unroll
;           for (int n = 0; n < 2; ++n) acc[a][b][m][n] = (f32x4){0.f, 0.f, 0.f, 0.f};
;     cur = nxt; cA = nA; cB = nB; ++ui;
;   }
;   G8_WAIT_V(0);
;   if (wr == 0) G8_BAR;
;   __device__ __forceinline__ void operator()(const f32x4 (&acc)[2][2][4][2], const g8::Unit& u, int ui, int wr, int wc, int fr, int fq) const {
;     ...
;         const int rl = 128 * ai + 64 * wr + 16 * m + fr;
;         const float r = rsl[ui * 256 + rl];
;         h16* rowp = hid + (size_t)(u.pm * 256 + rl) * DFF + 256 * u.pn + 32 * wc + 8 * fq;
; #pragma unroll
;         for (int bj = 0; bj < 2; ++bj) {
;           f32x4 v[2];
; #pragma unroll
;           for (int n = 0; n < 2; ++n) {
;             v[n] = acc[ai][bj][m][n] * r;
; #pragma unroll
;             for (int j = 0; j < 4; ++j) { const float t = fmaxf(v[n][j], 0.f); v[n][j] = t * t; }
;           }
;           __builtin_nontemporal_store(pack8(v[0], v[1]), (h16x8*)(rowp + 128 * bj));
;         }
	v_pk_mul_f32 v[32:33], v[32:33], v[34:35] op_sel_hi:[1,0]
	v_pk_mul_f32 v[30:31], v[30:31], v[34:35] op_sel_hi:[1,0]
	v_pk_mul_f32 v[26:27], v[26:27], v[34:35] op_sel_hi:[1,0]
	v_max_f32_e32 v40, 0, v30
	v_max_f32_e32 v30, 0, v31
	v_max_f32_e32 v31, 0, v32
	v_add_u32_e32 v36, s11, v156
	v_max_f32_e32 v32, 0, v33
	v_pk_mul_f32 v[28:29], v[28:29], v[34:35] op_sel_hi:[1,0]
	v_max_f32_e32 v33, 0, v26
	v_max_f32_e32 v38, 0, v27
	v_pk_mul_f32 v[26:27], v[30:31], v[30:31]
	v_ashrrev_i32_e32 v37, 31, v36
	v_max_f32_e32 v39, 0, v28
	v_fma_mixlo_f16 v28, v40, v40, 0
	v_cvt_pk_f16_f32 v27, v26, v27
	v_lshlrev_b64 v[36:37], 13, v[36:37]
	v_max_f32_e32 v41, 0, v29
	v_pack_b32_f16 v26, v28, v27
	v_pk_mul_f32 v[28:29], v[32:33], v[32:33]
	v_lshl_add_u64 v[36:37], s[0:1], 0, v[36:37]
	v_cvt_pk_f16_f32 v30, v28, v29
	v_pk_mul_f32 v[28:29], v[38:39], v[38:39]
	v_lshl_add_u64 v[36:37], v[36:37], 0, s[18:19]
	v_cvt_pk_f16_f32 v29, v28, v29
	v_lshl_add_u64 v[36:37], v[36:37], 0, s[92:93]
	v_alignbit_b32 v28, v29, v30, 16
	v_lshrrev_b32_e32 v29, 16, v29
	v_lshl_add_u64 v[36:37], v[36:37], 0, v[0:1]
	v_alignbit_b32 v27, v30, v27, 16
	v_fma_mixhi_f16 v29, v41, v41, 0
	v_pk_mul_f32 v[24:25], v[24:25], v[34:35] op_sel_hi:[1,0]
	v_pk_mul_f32 v[22:23], v[22:23], v[34:35] op_sel_hi:[1,0]
	global_store_dwordx4 v[36:37], v[26:29], off nt
	v_pk_mul_f32 v[18:19], v[18:19], v[34:35] op_sel_hi:[1,0]
	v_pk_mul_f32 v[20:21], v[20:21], v[34:35] op_sel_hi:[1,0]
	v_max_f32_e32 v28, 0, v22
	v_max_f32_e32 v22, 0, v23
	v_max_f32_e32 v23, 0, v24
	v_max_f32_e32 v24, 0, v25
	v_max_f32_e32 v25, 0, v18
	v_max_f32_e32 v26, 0, v19
	v_pk_mul_f32 v[18:19], v[22:23], v[22:23]
	v_max_f32_e32 v27, 0, v20
	v_fma_mixlo_f16 v20, v28, v28, 0
	v_cvt_pk_f16_f32 v19, v18, v19
	v_max_f32_e32 v29, 0, v21
	v_pack_b32_f16 v18, v20, v19
	v_pk_mul_f32 v[20:21], v[24:25], v[24:25]
	s_nop 0
	v_cvt_pk_f16_f32 v22, v20, v21
	v_pk_mul_f32 v[20:21], v[26:27], v[26:27]
	v_alignbit_b32 v19, v22, v19, 16
	v_cvt_pk_f16_f32 v21, v20, v21
	v_alignbit_b32 v20, v21, v22, 16
	v_lshrrev_b32_e32 v21, 16, v21
	v_fma_mixhi_f16 v21, v29, v29, 0
	global_store_dwordx4 v[36:37], v[18:21], off offset:256 nt
	s_nop 1
	v_mov_b32_e32 v20, v35
	v_pk_mul_f32 v[14:15], v[14:15], v[20:21] op_sel_hi:[1,0]
	v_pk_mul_f32 v[16:17], v[16:17], v[20:21] op_sel_hi:[1,0]
	v_max_f32_e32 v21, 0, v14
	v_max_f32_e32 v14, 0, v15
	v_max_f32_e32 v15, 0, v16
	v_pk_mul_f32 v[10:11], v[10:11], v[20:21] op_sel_hi:[1,0]
	v_add_u32_e32 v18, s11, v157
	v_max_f32_e32 v16, 0, v17
	v_pk_mul_f32 v[12:13], v[12:13], v[20:21] op_sel_hi:[1,0]
	v_max_f32_e32 v17, 0, v10
	v_max_f32_e32 v22, 0, v11
	v_pk_mul_f32 v[10:11], v[14:15], v[14:15]
	v_ashrrev_i32_e32 v19, 31, v18
	v_max_f32_e32 v23, 0, v12
	v_fma_mixlo_f16 v12, v21, v21, 0
	v_cvt_pk_f16_f32 v11, v10, v11
	v_lshlrev_b64 v[18:19], 13, v[18:19]
	v_max_f32_e32 v24, 0, v13
	v_pack_b32_f16 v10, v12, v11
	v_pk_mul_f32 v[12:13], v[16:17], v[16:17]
	v_lshl_add_u64 v[18:19], s[0:1], 0, v[18:19]
	v_cvt_pk_f16_f32 v14, v12, v13
	v_pk_mul_f32 v[12:13], v[22:23], v[22:23]
	v_lshl_add_u64 v[18:19], v[18:19], 0, s[18:19]
	v_cvt_pk_f16_f32 v13, v12, v13
	v_lshl_add_u64 v[18:19], v[18:19], 0, s[92:93]
	v_alignbit_b32 v12, v13, v14, 16
	v_lshrrev_b32_e32 v13, 16, v13
	v_lshl_add_u64 v[18:19], v[18:19], 0, v[0:1]
	v_alignbit_b32 v11, v14, v11, 16
	v_fma_mixhi_f16 v13, v24, v24, 0
	v_pk_mul_f32 v[8:9], v[8:9], v[20:21] op_sel_hi:[1,0]
	v_pk_mul_f32 v[6:7], v[6:7], v[20:21] op_sel_hi:[1,0]
	global_store_dwordx4 v[18:19], v[10:13], off nt
	v_pk_mul_f32 v[2:3], v[2:3], v[20:21] op_sel_hi:[1,0]
	v_pk_mul_f32 v[4:5], v[4:5], v[20:21] op_sel_hi:[1,0]
	v_max_f32_e32 v12, 0, v6
	v_max_f32_e32 v6, 0, v7
	v_max_f32_e32 v7, 0, v8
	v_max_f32_e32 v8, 0, v9
	v_max_f32_e32 v9, 0, v2
	v_max_f32_e32 v10, 0, v3
	v_pk_mul_f32 v[2:3], v[6:7], v[6:7]
	v_max_f32_e32 v11, 0, v4
	v_fma_mixlo_f16 v4, v12, v12, 0
	v_cvt_pk_f16_f32 v3, v2, v3
	v_max_f32_e32 v13, 0, v5
	v_pack_b32_f16 v2, v4, v3
	v_pk_mul_f32 v[4:5], v[8:9], v[8:9]
	s_mov_b64 s[18:19], s[14:15]
	v_cvt_pk_f16_f32 v6, v4, v5
	v_pk_mul_f32 v[4:5], v[10:11], v[10:11]
	v_alignbit_b32 v3, v6, v3, 16
	v_cvt_pk_f16_f32 v5, v4, v5
	v_alignbit_b32 v4, v5, v6, 16
	v_lshrrev_b32_e32 v5, 16, v5
	v_fma_mixhi_f16 v5, v13, v13, 0
	global_store_dwordx4 v[18:19], v[2:5], off offset:256 nt
	s_cbranch_vccz .LBB0_2466
	s_waitcnt vmcnt(0)
	s_cmpk_gt_u32 s2, 0xff
	s_cbranch_scc1 .LBB0_2477
	s_barrier

; #define G8_STAGE(bufoff, gbase) do { _Pragma("unroll") for (int _i = 0; _i < 2; ++_i) \
;     __builtin_amdgcn_global_load_lds((const unsigned*)((const char*)(gbase) + voffA[_i]), (LAS unsigned*)(lds + (bufoff) + ldsw + _i * 8192), 16, 0, 0); } while (0)
; #define G8_LDA(dst, b, h) do { _Pragma("unroll") for (int m = 0; m < 4; ++m) _Pragma("unroll") for (int k = 0; k < 2; ++k) dst[m][k] = *(const LAS h16x8*)(lds + G8_SA(b, h) + aoff + m * 2048 + k * 1024); } while (0)
; #define G8_LDB(dst, b, h) do { _Pragma("unroll") for (int n = 0; n < 2; ++n) _Pragma("unroll") for (int k = 0; k < 2; ++k) dst[n][k] = *(const LAS h16x8*)(lds + G8_SB(b, h) + boff + n * 2048 + k * 1024); } while (0)
; #define G8_MMA(ai, bj, At, Bt_) do { __builtin_amdgcn_s_setprio(1); _Pragma("unroll") for (int m = 0; m < 4; ++m) _Pragma("unroll") for (int n = 0; n < 2; ++n) _Pragma("unroll") for (int k = 0; k < 2; ++k) \
;     acc[ai][bj][m][n] = __builtin_amdgcn_mfma_f32_16x16x32_f16(Bt_[n][k], At[m][k], acc[ai][bj][m][n], 0, 0, 0); __builtin_amdgcn_s_setprio(0); } while (0)
; #define G8_WAIT_L(n) asm volatile("s_waitcnt lgkmcnt(" #n ")" ::: "memory")
; #define G8_BAR __builtin_amdgcn_s_barrier()
; #define G8_SCHED __builtin_amdgcn_sched_barrier(0)
; template <class Epi>
; __device__ __forceinline__ void gemm_phase(LAS unsigned char* lds, const h16* A, const h16* Bt, int K, const Order& S, const Epi& E) {
;     ...
;     for (int t = 0; t < nt; t += 2) {
;       const bool last = (t == nt - 2);
;       const char* a1 = cA + (size_t)(t + 1) * kstep;
;       const char* a2 = last ? nA : cA + (size_t)(t + 2) * kstep;
;       const char* b2 = last ? nB : cB + (size_t)(t + 2) * kstep;
;       const char* a3 = a2 + kstep;
;       const char* b3 = b2 + kstep;
;       if (Epi::MID_T >= 0 && t == Epi::MID_T) E.mid(acc, ui, wr, fr);
;       G8_LDB(B0, 0, 0); G8_SCHED; G8_LDA(At, 0, 0); G8_STAGE(G8_SA(1, 1), a1 + hstep);
;       G8_WAIT_L(8); G8_BAR; G8_WAIT_L(0); G8_MMA(0, 0, At, B0); G8_BAR; G8_SCHED;
;       G8_LDB(B1, 0, 1); G8_STAGE(G8_SB(0, 0), b2);
;       G8_BAR; G8_WAIT_L(0); G8_MMA(0, 1, At, B1); G8_BAR;
;       G8_LDA(At, 0, 1); G8_STAGE(G8_SA(0, 0), a2);
;       G8_BAR; G8_WAIT_L(0); G8_MMA(1, 0, At, B0); G8_BAR; G8_SCHED;
.LBB0_2542:
	s_add_u32 s24, s22, 0xfff00080
	s_addc_u32 s25, s23, -1
	s_cmp_eq_u32 s53, 60
	s_cselect_b32 s27, s3, s25
	s_cselect_b32 s26, s9, s24
	s_cselect_b32 s25, s15, s52
	s_cselect_b32 s24, s17, s51
	v_lshl_add_u64 v[140:141], s[22:23], 0, v[136:137]
	s_add_i32 m0, s35, 0xc000
	ds_read_b128 v[172:175], v135
	ds_read_b128 v[176:179], v135 offset:1024
	ds_read_b128 v[180:183], v135 offset:2048
	ds_read_b128 v[184:187], v135 offset:3072
	ds_read_b128 v[202:205], v135 offset:4096
	ds_read_b128 v[206:209], v135 offset:5120
	ds_read_b128 v[210:213], v135 offset:6144
	ds_read_b128 v[214:217], v135 offset:7168
	global_load_lds_dwordx4 v[140:141], off
	s_waitcnt lgkmcnt(8)
	s_barrier
	s_waitcnt lgkmcnt(0)
	s_setprio 1
	s_waitcnt lgkmcnt(0)
	v_mfma_f32_16x16x32_f16 v[126:129], v[152:155], v[172:175], v[126:129]
	v_mfma_f32_16x16x32_f16 v[122:125], v[164:167], v[172:175], v[122:125]
	v_mfma_f32_16x16x32_f16 v[110:113], v[152:155], v[180:183], v[110:113]
	v_mfma_f32_16x16x32_f16 v[106:109], v[164:167], v[180:183], v[106:109]
	v_mfma_f32_16x16x32_f16 v[94:97], v[152:155], v[202:205], v[94:97]
	v_mfma_f32_16x16x32_f16 v[90:93], v[164:167], v[202:205], v[90:93]
	v_mfma_f32_16x16x32_f16 v[78:81], v[152:155], v[210:213], v[78:81]
	v_mfma_f32_16x16x32_f16 v[74:77], v[164:167], v[210:213], v[74:77]
	v_lshl_add_u64 v[140:141], s[22:23], 0, v[138:139]
	s_add_i32 m0, s35, 0xe000
	s_nop 0
	global_load_lds_dwordx4 v[140:141], off
	v_mfma_f32_16x16x32_f16 v[126:129], v[160:163], v[176:179], v[126:129]
	v_mfma_f32_16x16x32_f16 v[122:125], v[168:171], v[176:179], v[122:125]
	v_mfma_f32_16x16x32_f16 v[110:113], v[160:163], v[184:187], v[110:113]
	v_mfma_f32_16x16x32_f16 v[106:109], v[168:171], v[184:187], v[106:109]
	v_mfma_f32_16x16x32_f16 v[94:97], v[160:163], v[206:209], v[94:97]
	v_mfma_f32_16x16x32_f16 v[90:93], v[168:171], v[206:209], v[90:93]
	v_mfma_f32_16x16x32_f16 v[78:81], v[160:163], v[214:217], v[78:81]
	v_mfma_f32_16x16x32_f16 v[74:77], v[168:171], v[214:217], v[74:77]
	s_setprio 0
	s_barrier
	v_or_b32_e32 v140, 0x14000, v158
	v_add_u32_e32 v141, 0x14400, v158
	ds_read_b128 v[218:221], v140
	ds_read_b128 v[222:225], v141
	v_add_u32_e32 v140, 0x14800, v158
	v_add_u32_e32 v141, 0x14c00, v158
	s_mov_b32 m0, s36
	ds_read_b128 v[226:229], v140
	ds_read_b128 v[230:233], v141
	v_lshl_add_u64 v[140:141], s[24:25], 0, v[0:1]
	global_load_lds_dwordx4 v[140:141], off
	s_barrier
	s_waitcnt lgkmcnt(0)
	s_setprio 1
	s_waitcnt lgkmcnt(0)
	v_mfma_f32_16x16x32_f16 v[118:121], v[218:221], v[172:175], v[118:121]
	v_mfma_f32_16x16x32_f16 v[114:117], v[226:229], v[172:175], v[114:117]
	v_mfma_f32_16x16x32_f16 v[102:105], v[218:221], v[180:183], v[102:105]
	v_mfma_f32_16x16x32_f16 v[98:101], v[226:229], v[180:183], v[98:101]
	v_mfma_f32_16x16x32_f16 v[86:89], v[218:221], v[202:205], v[86:89]
	v_mfma_f32_16x16x32_f16 v[82:85], v[226:229], v[202:205], v[82:85]
	v_mfma_f32_16x16x32_f16 v[70:73], v[218:221], v[210:213], v[70:73]
	v_mfma_f32_16x16x32_f16 v[66:69], v[226:229], v[210:213], v[66:69]
	v_lshl_add_u64 v[156:157], s[24:25], 0, v[130:131]
	s_mov_b32 m0, s37
	s_nop 0
	global_load_lds_dwordx4 v[156:157], off
	v_mfma_f32_16x16x32_f16 v[118:121], v[222:225], v[176:179], v[118:121]
	v_mfma_f32_16x16x32_f16 v[114:117], v[230:233], v[176:179], v[114:117]
	v_mfma_f32_16x16x32_f16 v[102:105], v[222:225], v[184:187], v[102:105]
	v_mfma_f32_16x16x32_f16 v[98:101], v[230:233], v[184:187], v[98:101]
	v_mfma_f32_16x16x32_f16 v[86:89], v[222:225], v[206:209], v[86:89]
	v_mfma_f32_16x16x32_f16 v[82:85], v[230:233], v[206:209], v[82:85]
	v_mfma_f32_16x16x32_f16 v[70:73], v[222:225], v[214:217], v[70:73]
	v_mfma_f32_16x16x32_f16 v[66:69], v[230:233], v[214:217], v[66:69]
	s_setprio 0
	s_mov_b32 m0, s35
	v_lshl_add_u64 v[188:189], s[26:27], 0, v[0:1]
	s_barrier
	ds_read_b128 v[172:175], v135 offset:16384
	ds_read_b128 v[176:179], v135 offset:17408
	ds_read_b128 v[180:183], v135 offset:18432
	ds_read_b128 v[184:187], v135 offset:19456
	ds_read_b128 v[202:205], v135 offset:20480
	ds_read_b128 v[206:209], v135 offset:21504
	ds_read_b128 v[210:213], v135 offset:22528
	ds_read_b128 v[214:217], v135 offset:23552
	global_load_lds_dwordx4 v[188:189], off
	s_waitcnt vmcnt(9)
	s_barrier
	s_waitcnt lgkmcnt(0)
	s_setprio 1
	s_waitcnt lgkmcnt(0)
	v_mfma_f32_16x16x32_f16 v[62:65], v[152:155], v[172:175], v[62:65]
	v_mfma_f32_16x16x32_f16 v[58:61], v[164:167], v[172:175], v[58:61]
	v_mfma_f32_16x16x32_f16 v[46:49], v[152:155], v[180:183], v[46:49]
	v_mfma_f32_16x16x32_f16 v[42:45], v[164:167], v[180:183], v[42:45]
	v_mfma_f32_16x16x32_f16 v[30:33], v[152:155], v[202:205], v[30:33]
	v_mfma_f32_16x16x32_f16 v[26:29], v[164:167], v[202:205], v[26:29]
	v_mfma_f32_16x16x32_f16 v[14:17], v[152:155], v[210:213], v[14:17]
	v_mfma_f32_16x16x32_f16 v[10:13], v[164:167], v[210:213], v[10:13]
	v_lshl_add_u64 v[234:235], s[26:27], 0, v[130:131]
	s_mov_b32 m0, s38
	s_nop 0
	global_load_lds_dwordx4 v[234:235], off
	v_mfma_f32_16x16x32_f16 v[62:65], v[160:163], v[176:179], v[62:65]
	v_mfma_f32_16x16x32_f16 v[58:61], v[168:171], v[176:179], v[58:61]
	v_mfma_f32_16x16x32_f16 v[46:49], v[160:163], v[184:187], v[46:49]
	v_mfma_f32_16x16x32_f16 v[42:45], v[168:171], v[184:187], v[42:45]
	v_mfma_f32_16x16x32_f16 v[30:33], v[160:163], v[206:209], v[30:33]
	v_mfma_f32_16x16x32_f16 v[26:29], v[168:171], v[206:209], v[26:29]
	v_mfma_f32_16x16x32_f16 v[14:17], v[160:163], v[214:217], v[14:17]
	v_mfma_f32_16x16x32_f16 v[10:13], v[168:171], v[214:217], v[10:13]
	s_setprio 0
	s_barrier
; #define G8_STAGE(bufoff, gbase) do { _Pragma("unroll") for (int _i = 0; _i < 2; ++_i) \
;     __builtin_amdgcn_global_load_lds((const unsigned*)((const char*)(gbase) + voffA[_i]), (LAS unsigned*)(lds + (bufoff) + ldsw + _i * 8192), 16, 0, 0); } while (0)
; #define G8_LDA(dst, b, h) do { _Pragma("unroll") for (int m = 0; m < 4; ++m) _Pragma("unroll") for (int k = 0; k < 2; ++k) dst[m][k] = *(const LAS h16x8*)(lds + G8_SA(b, h) + aoff + m * 2048 + k * 1024); } while (0)
; #define G8_LDB(dst, b, h) do { _Pragma("unroll") for (int n = 0; n < 2; ++n) _Pragma("unroll") for (int k = 0; k < 2; ++k) dst[n][k] = *(const LAS h16x8*)(lds + G8_SB(b, h) + boff + n * 2048 + k * 1024); } while (0)
; #define G8_MMA(ai, bj, At, Bt_) do { __builtin_amdgcn_s_setprio(1); _Pragma("unroll") for (int m = 0; m < 4; ++m) _Pragma("unroll") for (int n = 0; n < 2; ++n) _Pragma("unroll") for (int k = 0; k < 2; ++k) \
;     acc[ai][bj][m][n] = __builtin_amdgcn_mfma_f32_16x16x32_f16(Bt_[n][k], At[m][k], acc[ai][bj][m][n], 0, 0, 0); __builtin_amdgcn_s_setprio(0); } while (0)
; #define G8_WAIT_V(n) asm volatile("s_waitcnt vmcnt(" #n ")" ::: "memory")
; #define G8_WAIT_L(n) asm volatile("s_waitcnt lgkmcnt(" #n ")" ::: "memory")
; #define G8_BAR __builtin_amdgcn_s_barrier()
; #define G8_SCHED __builtin_amdgcn_sched_barrier(0)
; template <class Epi>
; __device__ __forceinline__ void gemm_phase(LAS unsigned char* lds, const h16* A, const h16* Bt, int K, const Order& S, const Epi& E) {
;     ...
;       G8_STAGE(G8_SB(0, 1), b2 + hstep);
;       G8_WAIT_V(6); G8_BAR; G8_MMA(1, 1, At, B1); G8_BAR;
;       G8_LDB(B0, 1, 0); G8_SCHED; G8_LDA(At, 1, 0); G8_STAGE(G8_SA(0, 1), a2 + hstep);
;       G8_WAIT_L(8); G8_BAR; G8_WAIT_L(0); G8_MMA(0, 0, At, B0); G8_BAR; G8_SCHED;
;       G8_LDB(B1, 1, 1); G8_STAGE(G8_SB(1, 0), b3);
;       G8_BAR; G8_WAIT_L(0); G8_MMA(0, 1, At, B1); G8_BAR;
;       G8_LDA(At, 1, 1); G8_STAGE(G8_SA(1, 0), a3);
	s_add_u32 s54, s24, 0x100000
	s_addc_u32 s55, s25, 0
	s_mov_b32 m0, s39
	v_lshl_add_u64 v[152:153], s[54:55], 0, v[0:1]
	global_load_lds_dwordx4 v[152:153], off
	v_lshl_add_u64 v[152:153], s[54:55], 0, v[130:131]
	s_mov_b32 m0, s40
	s_nop 0
	global_load_lds_dwordx4 v[152:153], off
	v_or_b32_e32 v152, 0x18000, v158
	v_add_u32_e32 v159, 0x18400, v158
	ds_read_b128 v[152:155], v152
	ds_read_b128 v[160:163], v159
	v_add_u32_e32 v159, 0x18800, v158
	v_add_u32_e32 v168, 0x18c00, v158
	ds_read_b128 v[164:167], v159
	ds_read_b128 v[168:171], v168
	s_waitcnt vmcnt(6)
	s_barrier
	s_setprio 1
	v_mfma_f32_16x16x32_f16 v[54:57], v[218:221], v[172:175], v[54:57]
	v_mfma_f32_16x16x32_f16 v[50:53], v[226:229], v[172:175], v[50:53]
	v_mfma_f32_16x16x32_f16 v[38:41], v[218:221], v[180:183], v[38:41]
	v_mfma_f32_16x16x32_f16 v[34:37], v[226:229], v[180:183], v[34:37]
	v_mfma_f32_16x16x32_f16 v[22:25], v[218:221], v[202:205], v[22:25]
	v_mfma_f32_16x16x32_f16 v[18:21], v[226:229], v[202:205], v[18:21]
	v_mfma_f32_16x16x32_f16 v[6:9], v[218:221], v[210:213], v[6:9]
	v_mfma_f32_16x16x32_f16 v[2:5], v[226:229], v[210:213], v[2:5]
	v_mfma_f32_16x16x32_f16 v[54:57], v[222:225], v[176:179], v[54:57]
	v_mfma_f32_16x16x32_f16 v[50:53], v[230:233], v[176:179], v[50:53]
	v_mfma_f32_16x16x32_f16 v[38:41], v[222:225], v[184:187], v[38:41]
	v_mfma_f32_16x16x32_f16 v[34:37], v[230:233], v[184:187], v[34:37]
	v_mfma_f32_16x16x32_f16 v[22:25], v[222:225], v[206:209], v[22:25]
	v_mfma_f32_16x16x32_f16 v[18:21], v[230:233], v[206:209], v[18:21]
	v_mfma_f32_16x16x32_f16 v[6:9], v[222:225], v[214:217], v[6:9]
	v_mfma_f32_16x16x32_f16 v[2:5], v[230:233], v[214:217], v[2:5]
	s_setprio 0
	s_barrier
	s_add_u32 s26, s26, 0x100000
	s_addc_u32 s27, s27, 0
	s_mov_b32 m0, s41
	v_lshl_add_u64 v[218:219], s[26:27], 0, v[0:1]
	ds_read_b128 v[172:175], v135 offset:32768
	ds_read_b128 v[176:179], v135 offset:33792
	ds_read_b128 v[180:183], v135 offset:34816
	ds_read_b128 v[184:187], v135 offset:35840
	ds_read_b128 v[202:205], v135 offset:36864
	ds_read_b128 v[206:209], v135 offset:37888
	ds_read_b128 v[210:213], v135 offset:38912
	ds_read_b128 v[214:217], v135 offset:39936
	global_load_lds_dwordx4 v[218:219], off
	s_waitcnt lgkmcnt(8)
	s_barrier
	s_waitcnt lgkmcnt(0)
	s_setprio 1
	s_waitcnt lgkmcnt(0)
	v_mfma_f32_16x16x32_f16 v[126:129], v[152:155], v[172:175], v[126:129]
	v_mfma_f32_16x16x32_f16 v[122:125], v[164:167], v[172:175], v[122:125]
	v_mfma_f32_16x16x32_f16 v[110:113], v[152:155], v[180:183], v[110:113]
	v_mfma_f32_16x16x32_f16 v[106:109], v[164:167], v[180:183], v[106:109]
	v_mfma_f32_16x16x32_f16 v[94:97], v[152:155], v[202:205], v[94:97]
	v_mfma_f32_16x16x32_f16 v[90:93], v[164:167], v[202:205], v[90:93]
	v_mfma_f32_16x16x32_f16 v[78:81], v[152:155], v[210:213], v[78:81]
	v_mfma_f32_16x16x32_f16 v[74:77], v[164:167], v[210:213], v[74:77]
	v_lshl_add_u64 v[218:219], s[26:27], 0, v[130:131]
	s_mov_b32 m0, s42
	s_nop 0
	global_load_lds_dwordx4 v[218:219], off
	v_mfma_f32_16x16x32_f16 v[126:129], v[160:163], v[176:179], v[126:129]
	v_mfma_f32_16x16x32_f16 v[122:125], v[168:171], v[176:179], v[122:125]
	v_mfma_f32_16x16x32_f16 v[110:113], v[160:163], v[184:187], v[110:113]
	v_mfma_f32_16x16x32_f16 v[106:109], v[168:171], v[184:187], v[106:109]
	v_mfma_f32_16x16x32_f16 v[94:97], v[160:163], v[206:209], v[94:97]
	v_mfma_f32_16x16x32_f16 v[90:93], v[168:171], v[206:209], v[90:93]
	v_mfma_f32_16x16x32_f16 v[78:81], v[160:163], v[214:217], v[78:81]
	v_mfma_f32_16x16x32_f16 v[74:77], v[168:171], v[214:217], v[74:77]
	s_setprio 0
	s_barrier
	v_or_b32_e32 v159, 0x1c000, v158
	s_mov_b32 m0, s44
	v_add_u32_e32 v195, 0x1c400, v158
	ds_read_b128 v[218:221], v159
	ds_read_b128 v[222:225], v195
	v_add_u32_e32 v159, 0x1c800, v158
	v_lshl_add_u64 v[140:141], v[140:141], 0, s[94:95]
	v_add_u32_e32 v195, 0x1cc00, v158
	ds_read_b128 v[226:229], v159
	ds_read_b128 v[230:233], v195
	global_load_lds_dwordx4 v[140:141], off
	s_barrier
	s_waitcnt lgkmcnt(0)
	s_setprio 1
	s_waitcnt lgkmcnt(0)
	v_mfma_f32_16x16x32_f16 v[118:121], v[218:221], v[172:175], v[118:121]
	v_mfma_f32_16x16x32_f16 v[114:117], v[226:229], v[172:175], v[114:117]
	v_mfma_f32_16x16x32_f16 v[102:105], v[218:221], v[180:183], v[102:105]
	v_mfma_f32_16x16x32_f16 v[98:101], v[226:229], v[180:183], v[98:101]
	v_mfma_f32_16x16x32_f16 v[86:89], v[218:221], v[202:205], v[86:89]
	v_mfma_f32_16x16x32_f16 v[82:85], v[226:229], v[202:205], v[82:85]
	v_mfma_f32_16x16x32_f16 v[70:73], v[218:221], v[210:213], v[70:73]
	v_mfma_f32_16x16x32_f16 v[66:69], v[226:229], v[210:213], v[66:69]
	v_lshl_add_u64 v[140:141], v[156:157], 0, s[94:95]
	s_mov_b32 m0, s45
	s_nop 0
	global_load_lds_dwordx4 v[140:141], off
	v_mfma_f32_16x16x32_f16 v[118:121], v[222:225], v[176:179], v[118:121]
	v_mfma_f32_16x16x32_f16 v[114:117], v[230:233], v[176:179], v[114:117]
	v_mfma_f32_16x16x32_f16 v[102:105], v[222:225], v[184:187], v[102:105]
	v_mfma_f32_16x16x32_f16 v[98:101], v[230:233], v[184:187], v[98:101]
	v_mfma_f32_16x16x32_f16 v[86:89], v[222:225], v[206:209], v[86:89]
	v_mfma_f32_16x16x32_f16 v[82:85], v[230:233], v[206:209], v[82:85]
	v_mfma_f32_16x16x32_f16 v[70:73], v[222:225], v[214:217], v[70:73]
	v_mfma_f32_16x16x32_f16 v[66:69], v[230:233], v[214:217], v[66:69]
	s_setprio 0
	s_mov_b32 m0, s46
	v_lshl_add_u64 v[140:141], v[188:189], 0, s[94:95]
	s_barrier
	ds_read_b128 v[172:175], v135 offset:49152
	ds_read_b128 v[176:179], v135 offset:50176
	ds_read_b128 v[180:183], v135 offset:51200
	ds_read_b128 v[184:187], v135 offset:52224
	ds_read_b128 v[202:205], v135 offset:53248
	ds_read_b128 v[206:209], v135 offset:54272
	ds_read_b128 v[210:213], v135 offset:55296
	ds_read_b128 v[214:217], v135 offset:56320
	global_load_lds_dwordx4 v[140:141], off
	s_waitcnt vmcnt(9)
	s_barrier
; #define G8_STAGE(bufoff, gbase) do { _Pragma("unroll") for (int _i = 0; _i < 2; ++_i) \
;     __builtin_amdgcn_global_load_lds((const unsigned*)((const char*)(gbase) + voffA[_i]), (LAS unsigned*)(lds + (bufoff) + ldsw + _i * 8192), 16, 0, 0); } while (0)
; #define G8_MMA(ai, bj, At, Bt_) do { __builtin_amdgcn_s_setprio(1); _Pragma("unroll") for (int m = 0; m < 4; ++m) _Pragma("unroll") for (int n = 0; n < 2; ++n) _Pragma("unroll") for (int k = 0; k < 2; ++k) \
;     acc[ai][bj][m][n] = __builtin_amdgcn_mfma_f32_16x16x32_f16(Bt_[n][k], At[m][k], acc[ai][bj][m][n], 0, 0, 0); __builtin_amdgcn_s_setprio(0); } while (0)
; #define G8_WAIT_V(n) asm volatile("s_waitcnt vmcnt(" #n ")" ::: "memory")
; #define G8_WAIT_L(n) asm volatile("s_waitcnt lgkmcnt(" #n ")" ::: "memory")
; #define G8_BAR __builtin_amdgcn_s_barrier()
; #define G8_SCHED __builtin_amdgcn_sched_barrier(0)
; template <class Epi>
; __device__ __forceinline__ void gemm_phase(LAS unsigned char* lds, const h16* A, const h16* Bt, int K, const Order& S, const Epi& E) {
;     ...
;       G8_BAR; G8_WAIT_L(0); G8_MMA(1, 0, At, B0); G8_BAR; G8_SCHED;
;       G8_STAGE(G8_SB(1, 1), b3 + hstep);
;       G8_WAIT_V(6); G8_BAR; G8_MMA(1, 1, At, B1); G8_BAR;
;   __device__ __forceinline__ void operator()(const f32x4 (&acc)[2][2][4][2], const g8::Unit& u, int ui, int wr, int wc, int fr, int fq) const {
; #pragma unroll
;     for (int ai = 0; ai < 2; ++ai)
; #pragma unroll
;       for (int m = 0; m < 4; ++m) {
;         const size_t row = (size_t)u.pm * 256 + 128 * ai + 64 * wr + 16 * m + fr;
;         const size_t base = row * DM + 256 * u.pn + 32 * wc + 8 * fq;
;         float ss = 0.f;
; #pragma unroll
;         for (int bj = 0; bj < 2; ++bj) {
;           const size_t idx = base + 128 * bj;
;           const h16x8 xv = *(const h16x8*)(xb + idx);
;           f32x4 x0 = acc[ai][bj][m][0], x1 = acc[ai][bj][m][1];
; #pragma unroll
;           for (int j = 0; j < 4; ++j) { x0[j] += (float)xv[j]; x1[j] += (float)xv[4 + j]; ss += x0[j] * x0[j] + x1[j] * x1[j]; }
;           if (final_out) {
;             __builtin_nontemporal_store(x0, (f32x4*)(xo + idx));
;             __builtin_nontemporal_store(x1, (f32x4*)(xo + idx + 4));
;           } else {
;             *(h16x8*)(xb + idx) = pack8(x0, x1);
;           }
	s_waitcnt lgkmcnt(0)
	s_setprio 1
	s_waitcnt lgkmcnt(0)
	v_mfma_f32_16x16x32_f16 v[62:65], v[152:155], v[172:175], v[62:65]
	v_mfma_f32_16x16x32_f16 v[58:61], v[164:167], v[172:175], v[58:61]
	v_mfma_f32_16x16x32_f16 v[46:49], v[152:155], v[180:183], v[46:49]
	v_mfma_f32_16x16x32_f16 v[42:45], v[164:167], v[180:183], v[42:45]
	v_mfma_f32_16x16x32_f16 v[30:33], v[152:155], v[202:205], v[30:33]
	v_mfma_f32_16x16x32_f16 v[26:29], v[164:167], v[202:205], v[26:29]
	v_mfma_f32_16x16x32_f16 v[14:17], v[152:155], v[210:213], v[14:17]
	v_mfma_f32_16x16x32_f16 v[10:13], v[164:167], v[210:213], v[10:13]
	v_lshl_add_u64 v[140:141], v[234:235], 0, s[94:95]
	s_mov_b32 m0, s47
	s_nop 0
	global_load_lds_dwordx4 v[140:141], off
	v_mfma_f32_16x16x32_f16 v[62:65], v[160:163], v[176:179], v[62:65]
	v_mfma_f32_16x16x32_f16 v[58:61], v[168:171], v[176:179], v[58:61]
	v_mfma_f32_16x16x32_f16 v[46:49], v[160:163], v[184:187], v[46:49]
	v_mfma_f32_16x16x32_f16 v[42:45], v[168:171], v[184:187], v[42:45]
	v_mfma_f32_16x16x32_f16 v[30:33], v[160:163], v[206:209], v[30:33]
	v_mfma_f32_16x16x32_f16 v[26:29], v[168:171], v[206:209], v[26:29]
	v_mfma_f32_16x16x32_f16 v[14:17], v[160:163], v[214:217], v[14:17]
	v_mfma_f32_16x16x32_f16 v[10:13], v[168:171], v[214:217], v[10:13]
	s_setprio 0
	s_barrier
	s_add_u32 s24, s24, 0x100080
	s_addc_u32 s25, s25, 0
	s_mov_b32 m0, s48
	v_lshl_add_u64 v[140:141], s[24:25], 0, v[0:1]
	global_load_lds_dwordx4 v[140:141], off
	v_lshl_add_u64 v[140:141], s[24:25], 0, v[130:131]
	s_mov_b32 m0, s49
	s_nop 0
	global_load_lds_dwordx4 v[140:141], off
	v_or_b32_e32 v140, 0x10000, v158
	v_add_u32_e32 v141, 0x10400, v158
	ds_read_b128 v[152:155], v140
	ds_read_b128 v[160:163], v141
	v_add_u32_e32 v140, 0x10800, v158
	v_add_u32_e32 v141, 0x10c00, v158
	ds_read_b128 v[164:167], v140
	ds_read_b128 v[168:171], v141
	s_waitcnt vmcnt(6)
	s_barrier
	s_setprio 1
	v_mfma_f32_16x16x32_f16 v[54:57], v[218:221], v[172:175], v[54:57]
	v_mfma_f32_16x16x32_f16 v[50:53], v[226:229], v[172:175], v[50:53]
	v_mfma_f32_16x16x32_f16 v[38:41], v[218:221], v[180:183], v[38:41]
	v_mfma_f32_16x16x32_f16 v[34:37], v[226:229], v[180:183], v[34:37]
	v_mfma_f32_16x16x32_f16 v[22:25], v[218:221], v[202:205], v[22:25]
	v_mfma_f32_16x16x32_f16 v[18:21], v[226:229], v[202:205], v[18:21]
	v_mfma_f32_16x16x32_f16 v[6:9], v[218:221], v[210:213], v[6:9]
	v_mfma_f32_16x16x32_f16 v[2:5], v[226:229], v[210:213], v[2:5]
	v_mfma_f32_16x16x32_f16 v[54:57], v[222:225], v[176:179], v[54:57]
	v_mfma_f32_16x16x32_f16 v[50:53], v[230:233], v[176:179], v[50:53]
	v_mfma_f32_16x16x32_f16 v[38:41], v[222:225], v[184:187], v[38:41]
	v_mfma_f32_16x16x32_f16 v[34:37], v[230:233], v[184:187], v[34:37]
	v_mfma_f32_16x16x32_f16 v[22:25], v[222:225], v[206:209], v[22:25]
	v_mfma_f32_16x16x32_f16 v[18:21], v[230:233], v[206:209], v[18:21]
	v_mfma_f32_16x16x32_f16 v[6:9], v[222:225], v[214:217], v[6:9]
	v_mfma_f32_16x16x32_f16 v[2:5], v[230:233], v[214:217], v[2:5]
	s_setprio 0
	s_add_i32 s53, s53, 2
	s_add_u32 s22, s22, 0x100
	s_addc_u32 s23, s23, 0
	s_add_u32 s51, s51, 0x100
	s_addc_u32 s52, s52, 0
	s_cmp_gt_u32 s53, 61
	s_barrier
	s_cbranch_scc0 .LBB0_2542
	s_waitcnt lgkmcnt(0)
	s_ashr_i32 s9, s8, 31
	s_lshl_b64 s[8:9], s[8:9], 8
	s_lshl_b32 s3, s2, 8
	v_lshl_add_u64 v[140:141], s[8:9], 0, v[132:133]
	s_ashr_i32 s8, s3, 31
	v_mov_b32_e32 v153, s8
	v_or_b32_e32 v152, s3, v134
	v_lshlrev_b64 v[154:155], 10, v[140:141]
	v_lshl_add_u64 v[156:157], v[154:155], 0, v[152:153]
	v_lshl_add_u64 v[154:155], v[156:157], 1, s[10:11]
	global_load_dwordx4 v[166:169], v[154:155], off
	global_load_dwordx4 v[170:173], v[154:155], off offset:256
	s_mov_b32 s9, 0
	s_mov_b32 s8, 0x8000
	v_lshl_add_u64 v[234:235], v[154:155], 0, s[8:9]
	global_load_dwordx4 v[174:177], v[234:235], off
	global_load_dwordx4 v[178:181], v[234:235], off offset:256
	s_mov_b32 s8, 0x10000
	v_lshl_add_u64 v[234:235], v[154:155], 0, s[8:9]
	global_load_dwordx4 v[182:185], v[234:235], off
	global_load_dwordx4 v[186:189], v[234:235], off offset:256
	s_mov_b32 s8, 0x18000
	v_lshl_add_u64 v[234:235], v[154:155], 0, s[8:9]
	global_load_dwordx4 v[202:205], v[234:235], off
	global_load_dwordx4 v[206:209], v[234:235], off offset:256
	s_mov_b32 s8, 0x40000
	v_lshl_add_u64 v[234:235], v[154:155], 0, s[8:9]
	global_load_dwordx4 v[210:213], v[234:235], off
	global_load_dwordx4 v[214:217], v[234:235], off offset:256
	s_mov_b32 s8, 0x48000
	v_lshl_add_u64 v[234:235], v[154:155], 0, s[8:9]
	global_load_dwordx4 v[218:221], v[234:235], off
	global_load_dwordx4 v[222:225], v[234:235], off offset:256
	s_mov_b32 s8, 0x50000
	v_lshl_add_u64 v[234:235], v[154:155], 0, s[8:9]
	global_load_dwordx4 v[226:229], v[234:235], off
	global_load_dwordx4 v[230:233], v[234:235], off offset:256
	s_mov_b64 s[8:9], -1
	s_and_b64 vcc, exec, s[0:1]
	s_waitcnt vmcnt(13)
	v_cvt_f32_f16_e32 v164, v166
	v_cvt_f32_f16_sdwa v165, v166 dst_sel:DWORD dst_unused:UNUSED_PAD src0_sel:WORD_1
	v_cvt_f32_f16_e32 v160, v167
	v_cvt_f32_f16_sdwa v161, v167 dst_sel:DWORD dst_unused:UNUSED_PAD src0_sel:WORD_1
	v_pk_add_f32 v[126:127], v[126:127], v[164:165]
	v_cvt_f32_f16_e32 v164, v168
	v_cvt_f32_f16_sdwa v165, v168 dst_sel:DWORD dst_unused:UNUSED_PAD src0_sel:WORD_1
	v_pk_add_f32 v[128:129], v[128:129], v[160:161]
	v_cvt_f32_f16_e32 v160, v169
	v_cvt_f32_f16_sdwa v161, v169 dst_sel:DWORD dst_unused:UNUSED_PAD src0_sel:WORD_1
	v_pk_add_f32 v[122:123], v[122:123], v[164:165]
	v_pk_add_f32 v[124:125], v[124:125], v[160:161]
	s_cbranch_vccz .LBB0_2545
	v_cvt_pk_f16_f32 v163, v124, v125
	v_cvt_pk_f16_f32 v162, v122, v123
	v_cvt_pk_f16_f32 v161, v128, v129
	v_cvt_pk_f16_f32 v160, v126, v127
	global_store_dwordx4 v[154:155], v[160:163], off
	s_mov_b64 s[8:9], 0
